# drop compiler vmcnt(0) at GEMM tile starts (in-loop counted waits suffice); hoist MLP-up epilogue row-stat loads to tile start
# speedup vs baseline: 1.0260x; 1.0011x over previous
.LBB0_550:
	s_add_u32 s59, s16, 0x100
	s_addc_u32 s60, s17, 0
	s_mov_b32 s61, -2
	s_waitcnt lgkmcnt(0)
	ds_read_b128 v[128:131], v188
	ds_read_b128 v[132:135], v188 offset:1024
	ds_read_b128 v[136:139], v188 offset:2048
	ds_read_b128 v[140:143], v188 offset:3072
	ds_read_b128 v[144:147], v189
	ds_read_b128 v[148:151], v189 offset:1024
	ds_read_b128 v[152:155], v189 offset:2048
	ds_read_b128 v[156:159], v189 offset:3072
	s_add_u32 s16, s0, 0x100
	s_addc_u32 s17, s1, 0
	s_cmp_eq_u32 s61, 16
	s_cselect_b32 s35, s7, s17
	s_cselect_b32 s34, s6, s16
	s_cselect_b32 s29, s15, s60
	s_cselect_b32 s28, s14, s59
	v_lshl_add_u64 v[220:221], s[0:1], 0, v[170:171]
	s_add_i32 m0, s39, 0xc000
	ds_read_b128 v[178:181], v190
	ds_read_b128 v[192:195], v190 offset:1024
	ds_read_b128 v[196:199], v190 offset:2048
	ds_read_b128 v[200:203], v190 offset:3072
	ds_read_b128 v[204:207], v190 offset:4096
	ds_read_b128 v[208:211], v190 offset:5120
	ds_read_b128 v[212:215], v190 offset:6144
	ds_read_b128 v[216:219], v190 offset:7168
	global_load_lds_dwordx4 v[220:221], off
	v_lshl_add_u64 v[220:221], s[0:1], 0, v[172:173]
	s_add_i32 m0, s39, 0xe000
	s_nop 0
	global_load_lds_dwordx4 v[220:221], off
	s_waitcnt vmcnt(8)
	s_waitcnt lgkmcnt(0)
	s_barrier
	s_setprio 1
	s_waitcnt lgkmcnt(0)
	v_mfma_f32_16x16x32_bf16 v[124:127], v[128:131], v[178:181], 0
	v_mfma_f32_16x16x32_bf16 v[120:123], v[136:139], v[178:181], 0
	v_mfma_f32_16x16x32_bf16 v[108:111], v[128:131], v[196:199], 0
	v_mfma_f32_16x16x32_bf16 v[104:107], v[136:139], v[196:199], 0
	v_mfma_f32_16x16x32_bf16 v[92:95], v[128:131], v[204:207], 0
	v_mfma_f32_16x16x32_bf16 v[88:91], v[136:139], v[204:207], 0
	v_mfma_f32_16x16x32_bf16 v[76:79], v[128:131], v[212:215], 0
	v_mfma_f32_16x16x32_bf16 v[72:75], v[136:139], v[212:215], 0
	v_mfma_f32_16x16x32_bf16 v[124:127], v[132:135], v[192:195], v[124:127]
	v_mfma_f32_16x16x32_bf16 v[120:123], v[140:143], v[192:195], v[120:123]
	v_mfma_f32_16x16x32_bf16 v[108:111], v[132:135], v[200:203], v[108:111]
	v_mfma_f32_16x16x32_bf16 v[104:107], v[140:143], v[200:203], v[104:107]
	v_mfma_f32_16x16x32_bf16 v[92:95], v[132:135], v[208:211], v[92:95]
	v_mfma_f32_16x16x32_bf16 v[88:91], v[140:143], v[208:211], v[88:91]
	v_mfma_f32_16x16x32_bf16 v[76:79], v[132:135], v[216:219], v[76:79]
	v_mfma_f32_16x16x32_bf16 v[72:75], v[140:143], v[216:219], v[72:75]
	s_setprio 0
	s_setprio 1
	v_mfma_f32_16x16x32_bf16 v[116:119], v[144:147], v[178:181], 0
	v_mfma_f32_16x16x32_bf16 v[112:115], v[152:155], v[178:181], 0
	v_mfma_f32_16x16x32_bf16 v[100:103], v[144:147], v[196:199], 0
	v_mfma_f32_16x16x32_bf16 v[96:99], v[152:155], v[196:199], 0
	v_mfma_f32_16x16x32_bf16 v[84:87], v[144:147], v[204:207], 0
	v_mfma_f32_16x16x32_bf16 v[80:83], v[152:155], v[204:207], 0
	v_mfma_f32_16x16x32_bf16 v[68:71], v[144:147], v[212:215], 0
	v_mfma_f32_16x16x32_bf16 v[64:67], v[152:155], v[212:215], 0
	v_mfma_f32_16x16x32_bf16 v[116:119], v[148:151], v[192:195], v[116:119]
	v_mfma_f32_16x16x32_bf16 v[112:115], v[156:159], v[192:195], v[112:115]
	v_mfma_f32_16x16x32_bf16 v[100:103], v[148:151], v[200:203], v[100:103]
	v_mfma_f32_16x16x32_bf16 v[96:99], v[156:159], v[200:203], v[96:99]
	v_mfma_f32_16x16x32_bf16 v[84:87], v[148:151], v[208:211], v[84:87]
	v_mfma_f32_16x16x32_bf16 v[80:83], v[156:159], v[208:211], v[80:83]
	v_mfma_f32_16x16x32_bf16 v[68:71], v[148:151], v[216:219], v[68:71]
	v_mfma_f32_16x16x32_bf16 v[64:67], v[156:159], v[216:219], v[64:67]
	s_setprio 0
	s_barrier
	s_add_i32 s0, s50, s38
	v_lshl_add_u64 v[220:221], s[28:29], 0, v[164:165]
	s_mov_b32 m0, s0
	ds_read_b128 v[178:181], v190 offset:16384
	ds_read_b128 v[192:195], v190 offset:17408
	ds_read_b128 v[196:199], v190 offset:18432
	ds_read_b128 v[200:203], v190 offset:19456
	ds_read_b128 v[204:207], v190 offset:20480
	ds_read_b128 v[208:211], v190 offset:21504
	ds_read_b128 v[212:215], v190 offset:22528
	ds_read_b128 v[216:219], v190 offset:23552
	global_load_lds_dwordx4 v[220:221], off
	s_add_i32 m0, s0, 0x2000
	s_add_u32 s0, s28, 0x50000
	v_lshl_add_u64 v[222:223], s[28:29], 0, v[168:169]
	s_addc_u32 s1, s29, 0
	s_add_i32 s62, s51, s38
	global_load_lds_dwordx4 v[222:223], off
	v_lshl_add_u64 v[224:225], s[0:1], 0, v[164:165]
	s_mov_b32 m0, s62
	v_lshl_add_u64 v[226:227], s[34:35], 0, v[166:167]
	global_load_lds_dwordx4 v[224:225], off
	v_lshl_add_u64 v[224:225], s[0:1], 0, v[168:169]
	s_add_i32 m0, s62, 0x2000
	s_nop 0
	global_load_lds_dwordx4 v[224:225], off
	v_lshl_add_u64 v[224:225], s[34:35], 0, v[162:163]
	s_mov_b32 m0, s39
	s_nop 0
	global_load_lds_dwordx4 v[224:225], off
	s_mov_b32 m0, s40
	s_nop 0
	global_load_lds_dwordx4 v[226:227], off
	s_waitcnt vmcnt(8)
	s_waitcnt lgkmcnt(0)
	s_barrier
	s_setprio 1
	s_waitcnt lgkmcnt(0)
	v_mfma_f32_16x16x32_bf16 v[60:63], v[128:131], v[178:181], 0
	v_mfma_f32_16x16x32_bf16 v[56:59], v[136:139], v[178:181], 0
	v_mfma_f32_16x16x32_bf16 v[44:47], v[128:131], v[196:199], 0
	v_mfma_f32_16x16x32_bf16 v[40:43], v[136:139], v[196:199], 0
	v_mfma_f32_16x16x32_bf16 v[28:31], v[128:131], v[204:207], 0
	v_mfma_f32_16x16x32_bf16 v[24:27], v[136:139], v[204:207], 0
	v_mfma_f32_16x16x32_bf16 v[12:15], v[128:131], v[212:215], 0
	v_mfma_f32_16x16x32_bf16 v[8:11], v[136:139], v[212:215], 0
	v_mfma_f32_16x16x32_bf16 v[60:63], v[132:135], v[192:195], v[60:63]
	v_mfma_f32_16x16x32_bf16 v[56:59], v[140:143], v[192:195], v[56:59]
	v_mfma_f32_16x16x32_bf16 v[44:47], v[132:135], v[200:203], v[44:47]
	v_mfma_f32_16x16x32_bf16 v[40:43], v[140:143], v[200:203], v[40:43]
	v_mfma_f32_16x16x32_bf16 v[28:31], v[132:135], v[208:211], v[28:31]
	v_mfma_f32_16x16x32_bf16 v[24:27], v[140:143], v[208:211], v[24:27]
	v_mfma_f32_16x16x32_bf16 v[12:15], v[132:135], v[216:219], v[12:15]
	v_mfma_f32_16x16x32_bf16 v[8:11], v[140:143], v[216:219], v[8:11]
	s_setprio 0
	s_setprio 1
	v_mfma_f32_16x16x32_bf16 v[52:55], v[144:147], v[178:181], 0
	v_mfma_f32_16x16x32_bf16 v[48:51], v[152:155], v[178:181], 0
	v_mfma_f32_16x16x32_bf16 v[36:39], v[144:147], v[196:199], 0
	v_mfma_f32_16x16x32_bf16 v[32:35], v[152:155], v[196:199], 0
	v_mfma_f32_16x16x32_bf16 v[20:23], v[144:147], v[204:207], 0
	v_mfma_f32_16x16x32_bf16 v[16:19], v[152:155], v[204:207], 0
	v_mfma_f32_16x16x32_bf16 v[4:7], v[144:147], v[212:215], 0
	v_mfma_f32_16x16x32_bf16 v[0:3], v[152:155], v[212:215], 0
	v_mfma_f32_16x16x32_bf16 v[52:55], v[148:151], v[192:195], v[52:55]
	v_mfma_f32_16x16x32_bf16 v[48:51], v[156:159], v[192:195], v[48:51]
	v_mfma_f32_16x16x32_bf16 v[36:39], v[148:151], v[200:203], v[36:39]
	v_mfma_f32_16x16x32_bf16 v[32:35], v[156:159], v[200:203], v[32:35]
	v_mfma_f32_16x16x32_bf16 v[20:23], v[148:151], v[208:211], v[20:23]
	v_mfma_f32_16x16x32_bf16 v[16:19], v[156:159], v[208:211], v[16:19]
	v_mfma_f32_16x16x32_bf16 v[4:7], v[148:151], v[216:219], v[4:7]
	v_mfma_f32_16x16x32_bf16 v[0:3], v[156:159], v[216:219], v[0:3]
	s_setprio 0
	s_barrier
	s_add_i32 s62, 0, 0x18000
	s_add_i32 s63, 0, 0x1c000
	v_add_u32_e32 v140, s62, v183
	v_add_u32_e32 v156, s63, v183
	ds_read_b128 v[128:131], v140
	ds_read_b128 v[132:135], v140 offset:1024
	ds_read_b128 v[136:139], v140 offset:2048
	ds_read_b128 v[140:143], v140 offset:3072
	ds_read_b128 v[144:147], v156
	ds_read_b128 v[148:151], v156 offset:1024
	ds_read_b128 v[152:155], v156 offset:2048
	ds_read_b128 v[156:159], v156 offset:3072
	s_add_u32 s0, s34, 0x50000
	s_addc_u32 s1, s35, 0
	s_mov_b32 m0, s41
	v_lshl_add_u64 v[228:229], s[0:1], 0, v[162:163]
	ds_read_b128 v[178:181], v190 offset:32768
	ds_read_b128 v[192:195], v190 offset:33792
	ds_read_b128 v[196:199], v190 offset:34816
	ds_read_b128 v[200:203], v190 offset:35840
	ds_read_b128 v[204:207], v190 offset:36864
	ds_read_b128 v[208:211], v190 offset:37888
	ds_read_b128 v[212:215], v190 offset:38912
	ds_read_b128 v[216:219], v190 offset:39936
	global_load_lds_dwordx4 v[228:229], off
	v_lshl_add_u64 v[228:229], s[0:1], 0, v[166:167]
	s_mov_b32 m0, s42
	s_nop 0
	global_load_lds_dwordx4 v[228:229], off
	s_waitcnt vmcnt(8)
	s_waitcnt lgkmcnt(0)
	s_barrier
	s_setprio 1
	s_waitcnt lgkmcnt(0)
	v_mfma_f32_16x16x32_bf16 v[124:127], v[128:131], v[178:181], v[124:127]
	v_mfma_f32_16x16x32_bf16 v[120:123], v[136:139], v[178:181], v[120:123]
	v_mfma_f32_16x16x32_bf16 v[108:111], v[128:131], v[196:199], v[108:111]
	v_mfma_f32_16x16x32_bf16 v[104:107], v[136:139], v[196:199], v[104:107]
	v_mfma_f32_16x16x32_bf16 v[92:95], v[128:131], v[204:207], v[92:95]
	v_mfma_f32_16x16x32_bf16 v[88:91], v[136:139], v[204:207], v[88:91]
	v_mfma_f32_16x16x32_bf16 v[76:79], v[128:131], v[212:215], v[76:79]
	v_mfma_f32_16x16x32_bf16 v[72:75], v[136:139], v[212:215], v[72:75]
	v_mfma_f32_16x16x32_bf16 v[124:127], v[132:135], v[192:195], v[124:127]
	v_mfma_f32_16x16x32_bf16 v[120:123], v[140:143], v[192:195], v[120:123]
	v_mfma_f32_16x16x32_bf16 v[108:111], v[132:135], v[200:203], v[108:111]
	v_mfma_f32_16x16x32_bf16 v[104:107], v[140:143], v[200:203], v[104:107]
	v_mfma_f32_16x16x32_bf16 v[92:95], v[132:135], v[208:211], v[92:95]
	v_mfma_f32_16x16x32_bf16 v[88:91], v[140:143], v[208:211], v[88:91]
	v_mfma_f32_16x16x32_bf16 v[76:79], v[132:135], v[216:219], v[76:79]
	v_mfma_f32_16x16x32_bf16 v[72:75], v[140:143], v[216:219], v[72:75]
	s_setprio 0
	s_setprio 1
	v_mfma_f32_16x16x32_bf16 v[116:119], v[144:147], v[178:181], v[116:119]
	v_mfma_f32_16x16x32_bf16 v[112:115], v[152:155], v[178:181], v[112:115]
	v_mfma_f32_16x16x32_bf16 v[100:103], v[144:147], v[196:199], v[100:103]
	v_mfma_f32_16x16x32_bf16 v[96:99], v[152:155], v[196:199], v[96:99]
	v_mfma_f32_16x16x32_bf16 v[84:87], v[144:147], v[204:207], v[84:87]
	v_mfma_f32_16x16x32_bf16 v[80:83], v[152:155], v[204:207], v[80:83]
	v_mfma_f32_16x16x32_bf16 v[68:71], v[144:147], v[212:215], v[68:71]
	v_mfma_f32_16x16x32_bf16 v[64:67], v[152:155], v[212:215], v[64:67]
	v_mfma_f32_16x16x32_bf16 v[116:119], v[148:151], v[192:195], v[116:119]
	v_mfma_f32_16x16x32_bf16 v[112:115], v[156:159], v[192:195], v[112:115]
	v_mfma_f32_16x16x32_bf16 v[100:103], v[148:151], v[200:203], v[100:103]
	v_mfma_f32_16x16x32_bf16 v[96:99], v[156:159], v[200:203], v[96:99]
	v_mfma_f32_16x16x32_bf16 v[84:87], v[148:151], v[208:211], v[84:87]
	v_mfma_f32_16x16x32_bf16 v[80:83], v[156:159], v[208:211], v[80:83]
	v_mfma_f32_16x16x32_bf16 v[68:71], v[148:151], v[216:219], v[68:71]
	v_mfma_f32_16x16x32_bf16 v[64:67], v[156:159], v[216:219], v[64:67]
	s_setprio 0
	s_barrier
	s_add_i32 s0, s62, s38
	v_lshl_add_u64 v[220:221], v[220:221], 0, s[10:11]
	s_mov_b32 m0, s0
	ds_read_b128 v[178:181], v190 offset:49152
	ds_read_b128 v[192:195], v190 offset:50176
	ds_read_b128 v[196:199], v190 offset:51200
	ds_read_b128 v[200:203], v190 offset:52224
	ds_read_b128 v[204:207], v190 offset:53248
	ds_read_b128 v[208:211], v190 offset:54272
	ds_read_b128 v[212:215], v190 offset:55296
	ds_read_b128 v[216:219], v190 offset:56320
	global_load_lds_dwordx4 v[220:221], off
	s_add_i32 m0, s0, 0x2000
	s_add_u32 s0, s28, 0x50080
	v_lshl_add_u64 v[220:221], v[222:223], 0, s[10:11]
	s_addc_u32 s1, s29, 0
	s_add_i32 s28, s63, s38
	global_load_lds_dwordx4 v[220:221], off
	v_lshl_add_u64 v[220:221], s[0:1], 0, v[164:165]
	s_mov_b32 m0, s28
	s_nop 0
	global_load_lds_dwordx4 v[220:221], off
	v_lshl_add_u64 v[220:221], s[0:1], 0, v[168:169]
	s_add_i32 m0, s28, 0x2000
	s_nop 0
	global_load_lds_dwordx4 v[220:221], off
	v_lshl_add_u64 v[220:221], v[224:225], 0, s[10:11]
	s_mov_b32 m0, s45
	s_nop 0
	global_load_lds_dwordx4 v[220:221], off
	v_lshl_add_u64 v[220:221], v[226:227], 0, s[10:11]
	s_mov_b32 m0, s46
	s_nop 0
	global_load_lds_dwordx4 v[220:221], off
	s_waitcnt vmcnt(8)
	s_waitcnt lgkmcnt(0)
	s_barrier
	s_setprio 1
	s_waitcnt lgkmcnt(0)
	v_mfma_f32_16x16x32_bf16 v[60:63], v[128:131], v[178:181], v[60:63]
	v_mfma_f32_16x16x32_bf16 v[56:59], v[136:139], v[178:181], v[56:59]
	v_mfma_f32_16x16x32_bf16 v[44:47], v[128:131], v[196:199], v[44:47]
	v_mfma_f32_16x16x32_bf16 v[40:43], v[136:139], v[196:199], v[40:43]
	v_mfma_f32_16x16x32_bf16 v[28:31], v[128:131], v[204:207], v[28:31]
	v_mfma_f32_16x16x32_bf16 v[24:27], v[136:139], v[204:207], v[24:27]
	v_mfma_f32_16x16x32_bf16 v[12:15], v[128:131], v[212:215], v[12:15]
	v_mfma_f32_16x16x32_bf16 v[8:11], v[136:139], v[212:215], v[8:11]
	v_mfma_f32_16x16x32_bf16 v[60:63], v[132:135], v[192:195], v[60:63]
	v_mfma_f32_16x16x32_bf16 v[56:59], v[140:143], v[192:195], v[56:59]
	v_mfma_f32_16x16x32_bf16 v[44:47], v[132:135], v[200:203], v[44:47]
	v_mfma_f32_16x16x32_bf16 v[40:43], v[140:143], v[200:203], v[40:43]
	v_mfma_f32_16x16x32_bf16 v[28:31], v[132:135], v[208:211], v[28:31]
	v_mfma_f32_16x16x32_bf16 v[24:27], v[140:143], v[208:211], v[24:27]
	v_mfma_f32_16x16x32_bf16 v[12:15], v[132:135], v[216:219], v[12:15]
	v_mfma_f32_16x16x32_bf16 v[8:11], v[140:143], v[216:219], v[8:11]
	s_setprio 0
	s_setprio 1
	v_mfma_f32_16x16x32_bf16 v[52:55], v[144:147], v[178:181], v[52:55]
	v_mfma_f32_16x16x32_bf16 v[48:51], v[152:155], v[178:181], v[48:51]
	v_mfma_f32_16x16x32_bf16 v[36:39], v[144:147], v[196:199], v[36:39]
	v_mfma_f32_16x16x32_bf16 v[32:35], v[152:155], v[196:199], v[32:35]
	v_mfma_f32_16x16x32_bf16 v[20:23], v[144:147], v[204:207], v[20:23]
	v_mfma_f32_16x16x32_bf16 v[16:19], v[152:155], v[204:207], v[16:19]
	v_mfma_f32_16x16x32_bf16 v[4:7], v[144:147], v[212:215], v[4:7]
	v_mfma_f32_16x16x32_bf16 v[0:3], v[152:155], v[212:215], v[0:3]
	v_mfma_f32_16x16x32_bf16 v[52:55], v[148:151], v[192:195], v[52:55]
	v_mfma_f32_16x16x32_bf16 v[48:51], v[156:159], v[192:195], v[48:51]
	v_mfma_f32_16x16x32_bf16 v[36:39], v[148:151], v[200:203], v[36:39]
	v_mfma_f32_16x16x32_bf16 v[32:35], v[156:159], v[200:203], v[32:35]
	v_mfma_f32_16x16x32_bf16 v[20:23], v[148:151], v[208:211], v[20:23]
	v_mfma_f32_16x16x32_bf16 v[16:19], v[156:159], v[208:211], v[16:19]
	v_mfma_f32_16x16x32_bf16 v[4:7], v[148:151], v[216:219], v[4:7]
	v_mfma_f32_16x16x32_bf16 v[0:3], v[156:159], v[216:219], v[0:3]
	s_setprio 0
	s_barrier
	s_add_i32 s61, s61, 2
	s_add_u32 s59, s59, 0x100
	s_addc_u32 s60, s60, 0
	s_cmp_gt_u32 s61, 17
	s_mov_b64 s[0:1], s[16:17]
	s_cbranch_scc0 .LBB0_551
	s_branch .Lpeel_exit_2

.LBB0_635:
	s_ashr_i32 s13, s12, 31
	s_lshl_b64 s[14:15], s[12:13], 19
	s_add_u32 s14, s64, s14
	s_addc_u32 s15, s65, s15
	s_and_b64 s[16:17], s[2:3], exec
	s_cselect_b32 s13, s15, s1
	s_cselect_b32 s48, s14, s0
	s_ashr_i32 s11, s10, 31
	s_lshl_b64 s[16:17], s[10:11], 19
	s_add_u32 s16, s36, s16
	s_addc_u32 s17, s37, s17
	s_and_b64 s[34:35], s[2:3], exec
	s_cselect_b32 s11, s17, s31
	s_cselect_b32 s49, s16, s30
	s_add_u32 s0, s0, 0x40080
	s_addc_u32 s1, s1, 0
	s_add_u32 s50, s30, 0x100
	s_addc_u32 s51, s31, 0
	s_mov_b32 s52, -2
	v_lshl_add_u32 v248, s28, 8, v156
	v_ashrrev_i32_e32 v249, 31, v248
	v_lshl_add_u64 v[248:249], v[248:249], 2, s[26:27]
	global_load_dword v240, v[248:249], off
	global_load_dword v241, v[248:249], off offset:64
	global_load_dword v242, v[248:249], off offset:128
	global_load_dword v243, v[248:249], off offset:192
	global_load_dword v244, v[248:249], off offset:512
	global_load_dword v245, v[248:249], off offset:576
	global_load_dword v246, v[248:249], off offset:640
	global_load_dword v247, v[248:249], off offset:704
	ds_read_b128 v[144:147], v159
	ds_read_b128 v[148:151], v159 offset:1024
	ds_read_b128 v[152:155], v159 offset:2048
	ds_read_b128 v[166:169], v159 offset:3072
	ds_read_b128 v[170:173], v162
	ds_read_b128 v[174:177], v162 offset:1024
	ds_read_b128 v[178:181], v162 offset:2048
	ds_read_b128 v[182:185], v162 offset:3072
	s_add_u32 s30, s0, 0xfffc0080
	s_addc_u32 s31, s1, -1
	s_cmp_eq_u32 s52, 12
	s_cselect_b32 s35, s13, s31
	s_cselect_b32 s34, s48, s30
	s_cselect_b32 s31, s11, s51
	s_cselect_b32 s30, s49, s50
	v_lshl_add_u64 v[218:219], s[0:1], 0, v[136:137]
	s_add_i32 m0, s29, 0xc000
	ds_read_b128 v[186:189], v163
	ds_read_b128 v[190:193], v163 offset:1024
	ds_read_b128 v[194:197], v163 offset:2048
	ds_read_b128 v[198:201], v163 offset:3072
	ds_read_b128 v[202:205], v163 offset:4096
	ds_read_b128 v[206:209], v163 offset:5120
	ds_read_b128 v[210:213], v163 offset:6144
	ds_read_b128 v[214:217], v163 offset:7168
	global_load_lds_dwordx4 v[218:219], off
	v_lshl_add_u64 v[218:219], s[0:1], 0, v[138:139]
	s_add_i32 m0, s29, 0xe000
	s_nop 0
	global_load_lds_dwordx4 v[218:219], off
	s_waitcnt vmcnt(8)
	s_waitcnt lgkmcnt(0)
	s_barrier
	s_setprio 1
	s_waitcnt lgkmcnt(0)
	v_mfma_f32_16x16x32_bf16 v[124:127], v[144:147], v[186:189], 0
	v_mfma_f32_16x16x32_bf16 v[120:123], v[152:155], v[186:189], 0
	v_mfma_f32_16x16x32_bf16 v[116:119], v[144:147], v[194:197], 0
	v_mfma_f32_16x16x32_bf16 v[104:107], v[152:155], v[194:197], 0
	v_mfma_f32_16x16x32_bf16 v[92:95], v[144:147], v[202:205], 0
	v_mfma_f32_16x16x32_bf16 v[88:91], v[152:155], v[202:205], 0
	v_mfma_f32_16x16x32_bf16 v[76:79], v[144:147], v[210:213], 0
	v_mfma_f32_16x16x32_bf16 v[72:75], v[152:155], v[210:213], 0
	v_mfma_f32_16x16x32_bf16 v[124:127], v[148:151], v[190:193], v[124:127]
	v_mfma_f32_16x16x32_bf16 v[120:123], v[166:169], v[190:193], v[120:123]
	v_mfma_f32_16x16x32_bf16 v[116:119], v[148:151], v[198:201], v[116:119]
	v_mfma_f32_16x16x32_bf16 v[104:107], v[166:169], v[198:201], v[104:107]
	v_mfma_f32_16x16x32_bf16 v[92:95], v[148:151], v[206:209], v[92:95]
	v_mfma_f32_16x16x32_bf16 v[88:91], v[166:169], v[206:209], v[88:91]
	v_mfma_f32_16x16x32_bf16 v[76:79], v[148:151], v[214:217], v[76:79]
	v_mfma_f32_16x16x32_bf16 v[72:75], v[166:169], v[214:217], v[72:75]
	s_setprio 0
	s_setprio 1
	v_mfma_f32_16x16x32_bf16 v[112:115], v[170:173], v[186:189], 0
	v_mfma_f32_16x16x32_bf16 v[108:111], v[178:181], v[186:189], 0
	v_mfma_f32_16x16x32_bf16 v[100:103], v[170:173], v[194:197], 0
	v_mfma_f32_16x16x32_bf16 v[96:99], v[178:181], v[194:197], 0
	v_mfma_f32_16x16x32_bf16 v[84:87], v[170:173], v[202:205], 0
	v_mfma_f32_16x16x32_bf16 v[80:83], v[178:181], v[202:205], 0
	v_mfma_f32_16x16x32_bf16 v[68:71], v[170:173], v[210:213], 0
	v_mfma_f32_16x16x32_bf16 v[64:67], v[178:181], v[210:213], 0
	v_mfma_f32_16x16x32_bf16 v[112:115], v[174:177], v[190:193], v[112:115]
	v_mfma_f32_16x16x32_bf16 v[108:111], v[182:185], v[190:193], v[108:111]
	v_mfma_f32_16x16x32_bf16 v[100:103], v[174:177], v[198:201], v[100:103]
	v_mfma_f32_16x16x32_bf16 v[96:99], v[182:185], v[198:201], v[96:99]
	v_mfma_f32_16x16x32_bf16 v[84:87], v[174:177], v[206:209], v[84:87]
	v_mfma_f32_16x16x32_bf16 v[80:83], v[182:185], v[206:209], v[80:83]
	v_mfma_f32_16x16x32_bf16 v[68:71], v[174:177], v[214:217], v[68:71]
	v_mfma_f32_16x16x32_bf16 v[64:67], v[182:185], v[214:217], v[64:67]
	s_setprio 0
	s_barrier
	s_add_i32 s53, s46, s38
	v_lshl_add_u64 v[218:219], s[30:31], 0, v[132:133]
	s_mov_b32 m0, s53
	ds_read_b128 v[186:189], v163 offset:16384
	ds_read_b128 v[190:193], v163 offset:17408
	ds_read_b128 v[194:197], v163 offset:18432
	ds_read_b128 v[198:201], v163 offset:19456
	ds_read_b128 v[202:205], v163 offset:20480
	ds_read_b128 v[206:209], v163 offset:21504
	ds_read_b128 v[210:213], v163 offset:22528
	ds_read_b128 v[214:217], v163 offset:23552
	global_load_lds_dwordx4 v[218:219], off
	s_add_i32 m0, s53, 0x2000
	s_add_u32 s54, s30, 0x40000
	v_lshl_add_u64 v[220:221], s[30:31], 0, v[128:129]
	s_addc_u32 s55, s31, 0
	s_add_i32 s53, s47, s38
	global_load_lds_dwordx4 v[220:221], off
	v_lshl_add_u64 v[222:223], s[54:55], 0, v[132:133]
	s_mov_b32 m0, s53
	v_lshl_add_u64 v[224:225], s[34:35], 0, v[130:131]
	global_load_lds_dwordx4 v[222:223], off
	v_lshl_add_u64 v[222:223], s[54:55], 0, v[128:129]
	s_add_i32 m0, s53, 0x2000
	s_nop 0
	global_load_lds_dwordx4 v[222:223], off
	v_lshl_add_u64 v[222:223], s[34:35], 0, v[134:135]
	s_mov_b32 m0, s29
	s_nop 0
	global_load_lds_dwordx4 v[222:223], off
	s_mov_b32 m0, s40
	s_nop 0
	global_load_lds_dwordx4 v[224:225], off
	s_waitcnt vmcnt(8)
	s_waitcnt lgkmcnt(0)
	s_barrier
	s_setprio 1
	s_waitcnt lgkmcnt(0)
	v_mfma_f32_16x16x32_bf16 v[60:63], v[144:147], v[186:189], 0
	v_mfma_f32_16x16x32_bf16 v[56:59], v[152:155], v[186:189], 0
	v_mfma_f32_16x16x32_bf16 v[44:47], v[144:147], v[194:197], 0
	v_mfma_f32_16x16x32_bf16 v[40:43], v[152:155], v[194:197], 0
	v_mfma_f32_16x16x32_bf16 v[28:31], v[144:147], v[202:205], 0
	v_mfma_f32_16x16x32_bf16 v[24:27], v[152:155], v[202:205], 0
	v_mfma_f32_16x16x32_bf16 v[12:15], v[144:147], v[210:213], 0
	v_mfma_f32_16x16x32_bf16 v[8:11], v[152:155], v[210:213], 0
	v_mfma_f32_16x16x32_bf16 v[60:63], v[148:151], v[190:193], v[60:63]
	v_mfma_f32_16x16x32_bf16 v[56:59], v[166:169], v[190:193], v[56:59]
	v_mfma_f32_16x16x32_bf16 v[44:47], v[148:151], v[198:201], v[44:47]
	v_mfma_f32_16x16x32_bf16 v[40:43], v[166:169], v[198:201], v[40:43]
	v_mfma_f32_16x16x32_bf16 v[28:31], v[148:151], v[206:209], v[28:31]
	v_mfma_f32_16x16x32_bf16 v[24:27], v[166:169], v[206:209], v[24:27]
	v_mfma_f32_16x16x32_bf16 v[12:15], v[148:151], v[214:217], v[12:15]
	v_mfma_f32_16x16x32_bf16 v[8:11], v[166:169], v[214:217], v[8:11]
	s_setprio 0
	s_setprio 1
	v_mfma_f32_16x16x32_bf16 v[52:55], v[170:173], v[186:189], 0
	v_mfma_f32_16x16x32_bf16 v[48:51], v[178:181], v[186:189], 0
	v_mfma_f32_16x16x32_bf16 v[36:39], v[170:173], v[194:197], 0
	v_mfma_f32_16x16x32_bf16 v[32:35], v[178:181], v[194:197], 0
	v_mfma_f32_16x16x32_bf16 v[20:23], v[170:173], v[202:205], 0
	v_mfma_f32_16x16x32_bf16 v[16:19], v[178:181], v[202:205], 0
	v_mfma_f32_16x16x32_bf16 v[4:7], v[170:173], v[210:213], 0
	v_mfma_f32_16x16x32_bf16 v[0:3], v[178:181], v[210:213], 0
	v_mfma_f32_16x16x32_bf16 v[52:55], v[174:177], v[190:193], v[52:55]
	v_mfma_f32_16x16x32_bf16 v[48:51], v[182:185], v[190:193], v[48:51]
	v_mfma_f32_16x16x32_bf16 v[36:39], v[174:177], v[198:201], v[36:39]
	v_mfma_f32_16x16x32_bf16 v[32:35], v[182:185], v[198:201], v[32:35]
	v_mfma_f32_16x16x32_bf16 v[20:23], v[174:177], v[206:209], v[20:23]
	v_mfma_f32_16x16x32_bf16 v[16:19], v[182:185], v[206:209], v[16:19]
	v_mfma_f32_16x16x32_bf16 v[4:7], v[174:177], v[214:217], v[4:7]
	v_mfma_f32_16x16x32_bf16 v[0:3], v[182:185], v[214:217], v[0:3]
	s_setprio 0
	s_barrier
	s_add_i32 s53, 0, 0x18000
	v_add_u32_e32 v165, s53, v157
	s_add_i32 s54, 0, 0x1c000
	ds_read_b128 v[144:147], v165
	ds_read_b128 v[148:151], v165 offset:1024
	ds_read_b128 v[152:155], v165 offset:2048
	ds_read_b128 v[166:169], v165 offset:3072
	v_add_u32_e32 v165, s54, v157
	ds_read_b128 v[170:173], v165
	ds_read_b128 v[174:177], v165 offset:1024
	ds_read_b128 v[178:181], v165 offset:2048
	ds_read_b128 v[182:185], v165 offset:3072
	s_add_u32 s34, s34, 0x40000
	s_addc_u32 s35, s35, 0
	s_mov_b32 m0, s41
	v_lshl_add_u64 v[226:227], s[34:35], 0, v[134:135]
	ds_read_b128 v[186:189], v163 offset:32768
	ds_read_b128 v[190:193], v163 offset:33792
	ds_read_b128 v[194:197], v163 offset:34816
	ds_read_b128 v[198:201], v163 offset:35840
	ds_read_b128 v[202:205], v163 offset:36864
	ds_read_b128 v[206:209], v163 offset:37888
	ds_read_b128 v[210:213], v163 offset:38912
	ds_read_b128 v[214:217], v163 offset:39936
	global_load_lds_dwordx4 v[226:227], off
	v_lshl_add_u64 v[226:227], s[34:35], 0, v[130:131]
	s_mov_b32 m0, s42
	s_nop 0
	global_load_lds_dwordx4 v[226:227], off
	s_waitcnt vmcnt(8)
	s_waitcnt lgkmcnt(0)
	s_barrier
	s_setprio 1
	s_waitcnt lgkmcnt(0)
	v_mfma_f32_16x16x32_bf16 v[124:127], v[144:147], v[186:189], v[124:127]
	v_mfma_f32_16x16x32_bf16 v[120:123], v[152:155], v[186:189], v[120:123]
	v_mfma_f32_16x16x32_bf16 v[116:119], v[144:147], v[194:197], v[116:119]
	v_mfma_f32_16x16x32_bf16 v[104:107], v[152:155], v[194:197], v[104:107]
	v_mfma_f32_16x16x32_bf16 v[92:95], v[144:147], v[202:205], v[92:95]
	v_mfma_f32_16x16x32_bf16 v[88:91], v[152:155], v[202:205], v[88:91]
	v_mfma_f32_16x16x32_bf16 v[76:79], v[144:147], v[210:213], v[76:79]
	v_mfma_f32_16x16x32_bf16 v[72:75], v[152:155], v[210:213], v[72:75]
	v_mfma_f32_16x16x32_bf16 v[124:127], v[148:151], v[190:193], v[124:127]
	v_mfma_f32_16x16x32_bf16 v[120:123], v[166:169], v[190:193], v[120:123]
	v_mfma_f32_16x16x32_bf16 v[116:119], v[148:151], v[198:201], v[116:119]
	v_mfma_f32_16x16x32_bf16 v[104:107], v[166:169], v[198:201], v[104:107]
	v_mfma_f32_16x16x32_bf16 v[92:95], v[148:151], v[206:209], v[92:95]
	v_mfma_f32_16x16x32_bf16 v[88:91], v[166:169], v[206:209], v[88:91]
	v_mfma_f32_16x16x32_bf16 v[76:79], v[148:151], v[214:217], v[76:79]
	v_mfma_f32_16x16x32_bf16 v[72:75], v[166:169], v[214:217], v[72:75]
	s_setprio 0
	s_setprio 1
	v_mfma_f32_16x16x32_bf16 v[112:115], v[170:173], v[186:189], v[112:115]
	v_mfma_f32_16x16x32_bf16 v[108:111], v[178:181], v[186:189], v[108:111]
	v_mfma_f32_16x16x32_bf16 v[100:103], v[170:173], v[194:197], v[100:103]
	v_mfma_f32_16x16x32_bf16 v[96:99], v[178:181], v[194:197], v[96:99]
	v_mfma_f32_16x16x32_bf16 v[84:87], v[170:173], v[202:205], v[84:87]
	v_mfma_f32_16x16x32_bf16 v[80:83], v[178:181], v[202:205], v[80:83]
	v_mfma_f32_16x16x32_bf16 v[68:71], v[170:173], v[210:213], v[68:71]
	v_mfma_f32_16x16x32_bf16 v[64:67], v[178:181], v[210:213], v[64:67]
	v_mfma_f32_16x16x32_bf16 v[112:115], v[174:177], v[190:193], v[112:115]
	v_mfma_f32_16x16x32_bf16 v[108:111], v[182:185], v[190:193], v[108:111]
	v_mfma_f32_16x16x32_bf16 v[100:103], v[174:177], v[198:201], v[100:103]
	v_mfma_f32_16x16x32_bf16 v[96:99], v[182:185], v[198:201], v[96:99]
	v_mfma_f32_16x16x32_bf16 v[84:87], v[174:177], v[206:209], v[84:87]
	v_mfma_f32_16x16x32_bf16 v[80:83], v[182:185], v[206:209], v[80:83]
	v_mfma_f32_16x16x32_bf16 v[68:71], v[174:177], v[214:217], v[68:71]
	v_mfma_f32_16x16x32_bf16 v[64:67], v[182:185], v[214:217], v[64:67]
	s_setprio 0
	s_barrier
	s_add_i32 s34, s53, s38
	v_lshl_add_u64 v[218:219], v[218:219], 0, s[6:7]
	s_mov_b32 m0, s34
	ds_read_b128 v[186:189], v163 offset:49152
	ds_read_b128 v[190:193], v163 offset:50176
	ds_read_b128 v[194:197], v163 offset:51200
	ds_read_b128 v[198:201], v163 offset:52224
	ds_read_b128 v[202:205], v163 offset:53248
	ds_read_b128 v[206:209], v163 offset:54272
	ds_read_b128 v[210:213], v163 offset:55296
	ds_read_b128 v[214:217], v163 offset:56320
	global_load_lds_dwordx4 v[218:219], off
	s_add_i32 m0, s34, 0x2000
	s_add_u32 s30, s30, 0x40080
	v_lshl_add_u64 v[218:219], v[220:221], 0, s[6:7]
	s_addc_u32 s31, s31, 0
	s_add_i32 s34, s54, s38
	global_load_lds_dwordx4 v[218:219], off
	v_lshl_add_u64 v[218:219], s[30:31], 0, v[132:133]
	s_mov_b32 m0, s34
	s_nop 0
	global_load_lds_dwordx4 v[218:219], off
	v_lshl_add_u64 v[218:219], s[30:31], 0, v[128:129]
	s_add_i32 m0, s34, 0x2000
	s_nop 0
	global_load_lds_dwordx4 v[218:219], off
	v_lshl_add_u64 v[218:219], v[222:223], 0, s[6:7]
	s_mov_b32 m0, s44
	s_nop 0
	global_load_lds_dwordx4 v[218:219], off
	v_lshl_add_u64 v[218:219], v[224:225], 0, s[6:7]
	s_mov_b32 m0, s45
	s_nop 0
	global_load_lds_dwordx4 v[218:219], off
	s_waitcnt vmcnt(8)
	s_waitcnt lgkmcnt(0)
	s_barrier
	s_setprio 1
	s_waitcnt lgkmcnt(0)
	v_mfma_f32_16x16x32_bf16 v[60:63], v[144:147], v[186:189], v[60:63]
	v_mfma_f32_16x16x32_bf16 v[56:59], v[152:155], v[186:189], v[56:59]
	v_mfma_f32_16x16x32_bf16 v[44:47], v[144:147], v[194:197], v[44:47]
	v_mfma_f32_16x16x32_bf16 v[40:43], v[152:155], v[194:197], v[40:43]
	v_mfma_f32_16x16x32_bf16 v[28:31], v[144:147], v[202:205], v[28:31]
	v_mfma_f32_16x16x32_bf16 v[24:27], v[152:155], v[202:205], v[24:27]
	v_mfma_f32_16x16x32_bf16 v[12:15], v[144:147], v[210:213], v[12:15]
	v_mfma_f32_16x16x32_bf16 v[8:11], v[152:155], v[210:213], v[8:11]
	v_mfma_f32_16x16x32_bf16 v[60:63], v[148:151], v[190:193], v[60:63]
	v_mfma_f32_16x16x32_bf16 v[56:59], v[166:169], v[190:193], v[56:59]
	v_mfma_f32_16x16x32_bf16 v[44:47], v[148:151], v[198:201], v[44:47]
	v_mfma_f32_16x16x32_bf16 v[40:43], v[166:169], v[198:201], v[40:43]
	v_mfma_f32_16x16x32_bf16 v[28:31], v[148:151], v[206:209], v[28:31]
	v_mfma_f32_16x16x32_bf16 v[24:27], v[166:169], v[206:209], v[24:27]
	v_mfma_f32_16x16x32_bf16 v[12:15], v[148:151], v[214:217], v[12:15]
	v_mfma_f32_16x16x32_bf16 v[8:11], v[166:169], v[214:217], v[8:11]
	s_setprio 0
	s_setprio 1
	v_mfma_f32_16x16x32_bf16 v[52:55], v[170:173], v[186:189], v[52:55]
	v_mfma_f32_16x16x32_bf16 v[48:51], v[178:181], v[186:189], v[48:51]
	v_mfma_f32_16x16x32_bf16 v[36:39], v[170:173], v[194:197], v[36:39]
	v_mfma_f32_16x16x32_bf16 v[32:35], v[178:181], v[194:197], v[32:35]
	v_mfma_f32_16x16x32_bf16 v[20:23], v[170:173], v[202:205], v[20:23]
	v_mfma_f32_16x16x32_bf16 v[16:19], v[178:181], v[202:205], v[16:19]
	v_mfma_f32_16x16x32_bf16 v[4:7], v[170:173], v[210:213], v[4:7]
	v_mfma_f32_16x16x32_bf16 v[0:3], v[178:181], v[210:213], v[0:3]
	v_mfma_f32_16x16x32_bf16 v[52:55], v[174:177], v[190:193], v[52:55]
	v_mfma_f32_16x16x32_bf16 v[48:51], v[182:185], v[190:193], v[48:51]
	v_mfma_f32_16x16x32_bf16 v[36:39], v[174:177], v[198:201], v[36:39]
	v_mfma_f32_16x16x32_bf16 v[32:35], v[182:185], v[198:201], v[32:35]
	v_mfma_f32_16x16x32_bf16 v[20:23], v[174:177], v[206:209], v[20:23]
	v_mfma_f32_16x16x32_bf16 v[16:19], v[182:185], v[206:209], v[16:19]
	v_mfma_f32_16x16x32_bf16 v[4:7], v[174:177], v[214:217], v[4:7]
	v_mfma_f32_16x16x32_bf16 v[0:3], v[182:185], v[214:217], v[0:3]
	s_setprio 0
	s_barrier
	s_add_i32 s52, s52, 2
	s_add_u32 s0, s0, 0x100
	s_addc_u32 s1, s1, 0
	s_add_u32 s50, s50, 0x100
	s_addc_u32 s51, s51, 0
	s_cmp_gt_u32 s52, 13
	s_cbranch_scc0 .LBB0_636
	s_branch .Lpeel_exit_3

.LBB0_639:
	v_lshl_add_u32 v146, s28, 8, v156
	v_ashrrev_i32_e32 v147, 31, v146
	v_lshl_add_u64 v[144:145], v[146:147], 2, s[26:27]
	v_or_b32_e32 v166, 16, v146
	v_ashrrev_i32_e32 v167, 31, v166
	v_lshl_add_u64 v[144:145], v[166:167], 2, s[26:27]
	v_lshl_or_b32 v168, s33, 8, v158
	v_or_b32_e32 v170, 32, v146
	v_or_b32_e32 v154, 48, v146
	v_add_u32_e32 v148, 0xa0, v146
	v_add_u32_e32 v152, 0x80, v146
	v_add_u32_e32 v150, 0x90, v146
	v_add_u32_e32 v144, 0xb0, v146
	v_ashrrev_i32_e32 v169, 31, v168
	v_ashrrev_i32_e32 v171, 31, v170
	v_ashrrev_i32_e32 v155, 31, v154
	v_ashrrev_i32_e32 v149, 31, v148
	v_ashrrev_i32_e32 v153, 31, v152
	v_ashrrev_i32_e32 v151, 31, v150
	v_ashrrev_i32_e32 v145, 31, v144
	v_lshlrev_b64 v[172:173], 13, v[146:147]
	v_lshlrev_b64 v[146:147], 1, v[168:169]
	v_lshl_add_u64 v[168:169], v[170:171], 2, s[26:27]
	v_lshl_add_u64 v[174:175], v[154:155], 2, s[26:27]
	v_lshl_add_u64 v[180:181], v[148:149], 2, s[26:27]
	v_lshl_add_u64 v[176:177], v[152:153], 2, s[26:27]
	v_lshl_add_u64 v[178:179], v[150:151], 2, s[26:27]
	v_lshl_add_u64 v[182:183], v[144:145], 2, s[26:27]
	s_nop 0
	s_nop 0
	s_nop 0
	s_nop 0
	v_lshl_add_u64 v[172:173], s[92:93], 0, v[172:173]
	v_lshl_add_u64 v[172:173], v[172:173], 0, v[146:147]
	v_lshlrev_b64 v[166:167], 13, v[166:167]
	s_andn2_b64 vcc, exec, s[2:3]
	s_mov_b64 s[0:1], -1
	v_fmamk_f32 v168, v240, 0x3a800000, v164
	v_rsq_f32_e32 v168, v168
	v_fmamk_f32 v169, v241, 0x3a800000, v164
	v_rsq_f32_e32 v174, v169
	v_pk_mul_f32 v[126:127], v[126:127], v[168:169] op_sel_hi:[1,0]
	v_pk_mul_f32 v[124:125], v[124:125], v[168:169] op_sel_hi:[1,0]
	v_pk_mul_f32 v[122:123], v[122:123], v[168:169] op_sel_hi:[1,0]
	v_pk_mul_f32 v[120:121], v[120:121], v[168:169] op_sel_hi:[1,0]
	v_pk_mul_f32 v[114:115], v[114:115], v[168:169] op_sel_hi:[1,0]
	v_pk_mul_f32 v[112:113], v[112:113], v[168:169] op_sel_hi:[1,0]
	v_pk_mul_f32 v[110:111], v[110:111], v[168:169] op_sel_hi:[1,0]
	v_pk_mul_f32 v[108:109], v[108:109], v[168:169] op_sel_hi:[1,0]
	v_max_f32_e32 v124, 0, v124
	v_max_f32_e32 v120, 0, v120
	v_max_f32_e32 v125, 0, v125
	v_max_f32_e32 v121, 0, v121
	v_max_f32_e32 v126, 0, v126
	v_max_f32_e32 v122, 0, v122
	v_max_f32_e32 v127, 0, v127
	v_max_f32_e32 v123, 0, v123
	v_max_f32_e32 v112, 0, v112
	v_max_f32_e32 v113, 0, v113
	v_max_f32_e32 v114, 0, v114
	v_max_f32_e32 v115, 0, v115
	v_max_f32_e32 v108, 0, v108
	v_max_f32_e32 v109, 0, v109
	v_max_f32_e32 v110, 0, v110
	v_max_f32_e32 v111, 0, v111
	v_pk_mul_f32 v[168:169], v[106:107], v[174:175] op_sel_hi:[1,0]
	v_pk_mul_f32 v[104:105], v[104:105], v[174:175] op_sel_hi:[1,0]
	v_pk_mul_f32 v[106:107], v[124:125], v[124:125]
	v_pk_mul_f32 v[120:121], v[120:121], v[120:121]
	v_pk_mul_f32 v[124:125], v[126:127], v[126:127]
	v_pk_mul_f32 v[122:123], v[122:123], v[122:123]
	v_pk_mul_f32 v[112:113], v[112:113], v[112:113]
	v_pk_mul_f32 v[114:115], v[114:115], v[114:115]
	v_pk_mul_f32 v[118:119], v[118:119], v[174:175] op_sel_hi:[1,0]
	v_pk_mul_f32 v[116:117], v[116:117], v[174:175] op_sel_hi:[1,0]
	v_pk_mul_f32 v[126:127], v[108:109], v[108:109]
	v_pk_mul_f32 v[176:177], v[110:111], v[110:111]
	v_max_f32_e32 v178, 0, v104
	v_max_f32_e32 v179, 0, v105
	v_cvt_pk_bf16_f32 v104, v106, v107
	v_cvt_pk_bf16_f32 v105, v124, v125
	v_cvt_pk_bf16_f32 v106, v120, v121
	v_cvt_pk_bf16_f32 v107, v122, v123
	v_cvt_pk_bf16_f32 v108, v112, v113
	v_cvt_pk_bf16_f32 v109, v114, v115
	v_max_f32_e32 v116, 0, v116
	v_max_f32_e32 v117, 0, v117
	v_cvt_pk_bf16_f32 v110, v126, v127
	v_cvt_pk_bf16_f32 v111, v176, v177
	global_store_dwordx4 v[172:173], v[104:107], off
	global_store_dwordx4 v[172:173], v[108:111], off offset:256
	v_pk_mul_f32 v[100:101], v[100:101], v[174:175] op_sel_hi:[1,0]
	v_pk_mul_f32 v[104:105], v[116:117], v[116:117]
	v_max_f32_e32 v108, 0, v118
	v_max_f32_e32 v109, 0, v119
	v_max_f32_e32 v110, 0, v168
	v_max_f32_e32 v111, 0, v169
	v_pk_mul_f32 v[108:109], v[108:109], v[108:109]
	v_pk_mul_f32 v[106:107], v[178:179], v[178:179]
	v_pk_mul_f32 v[110:111], v[110:111], v[110:111]
	v_cvt_pk_bf16_f32 v104, v104, v105
	v_cvt_pk_bf16_f32 v105, v108, v109
	v_lshl_add_u64 v[108:109], s[92:93], 0, v[166:167]
	v_pk_mul_f32 v[98:99], v[98:99], v[174:175] op_sel_hi:[1,0]
	v_pk_mul_f32 v[96:97], v[96:97], v[174:175] op_sel_hi:[1,0]
	v_cvt_pk_bf16_f32 v106, v106, v107
	v_cvt_pk_bf16_f32 v107, v110, v111
	v_lshl_add_u64 v[108:109], v[108:109], 0, v[146:147]
	v_pk_mul_f32 v[102:103], v[102:103], v[174:175] op_sel_hi:[1,0]
	v_max_f32_e32 v100, 0, v100
	v_max_f32_e32 v96, 0, v96
	v_max_f32_e32 v101, 0, v101
	v_max_f32_e32 v97, 0, v97
	v_max_f32_e32 v98, 0, v98
	v_max_f32_e32 v99, 0, v99
	global_store_dwordx4 v[108:109], v[104:107], off
	v_pk_mul_f32 v[100:101], v[100:101], v[100:101]
	s_nop 0
	v_pk_mul_f32 v[104:105], v[96:97], v[96:97]
	v_max_f32_e32 v96, 0, v102
	v_max_f32_e32 v97, 0, v103
	v_pk_mul_f32 v[106:107], v[98:99], v[98:99]
	v_fmamk_f32 v99, v242, 0x3a800000, v164
	v_pk_mul_f32 v[102:103], v[96:97], v[96:97]
	v_cvt_pk_bf16_f32 v96, v100, v101
	v_rsq_f32_e32 v100, v99
	v_cvt_pk_bf16_f32 v97, v102, v103
	v_cvt_pk_bf16_f32 v98, v104, v105
	v_cvt_pk_bf16_f32 v99, v106, v107
	v_pk_mul_f32 v[92:93], v[92:93], v[100:101] op_sel_hi:[1,0]
	v_pk_mul_f32 v[88:89], v[88:89], v[100:101] op_sel_hi:[1,0]
	v_pk_mul_f32 v[94:95], v[94:95], v[100:101] op_sel_hi:[1,0]
	v_pk_mul_f32 v[90:91], v[90:91], v[100:101] op_sel_hi:[1,0]
	v_max_f32_e32 v92, 0, v92
	v_max_f32_e32 v88, 0, v88
	v_max_f32_e32 v93, 0, v93
	v_max_f32_e32 v89, 0, v89
	global_store_dwordx4 v[108:109], v[96:99], off offset:256
	v_pk_mul_f32 v[92:93], v[92:93], v[92:93]
	v_max_f32_e32 v90, 0, v90
	v_lshlrev_b64 v[96:97], 13, v[170:171]
	v_pk_mul_f32 v[98:99], v[88:89], v[88:89]
	v_max_f32_e32 v88, 0, v94
	v_max_f32_e32 v89, 0, v95
	v_max_f32_e32 v91, 0, v91
	v_pk_mul_f32 v[94:95], v[88:89], v[88:89]
	v_pk_mul_f32 v[102:103], v[90:91], v[90:91]
	v_cvt_pk_bf16_f32 v88, v92, v93
	v_lshl_add_u64 v[92:93], s[92:93], 0, v[96:97]
	v_pk_mul_f32 v[84:85], v[84:85], v[100:101] op_sel_hi:[1,0]
	v_pk_mul_f32 v[82:83], v[82:83], v[100:101] op_sel_hi:[1,0]
	v_pk_mul_f32 v[80:81], v[80:81], v[100:101] op_sel_hi:[1,0]
	v_cvt_pk_bf16_f32 v89, v94, v95
	v_cvt_pk_bf16_f32 v90, v98, v99
	v_cvt_pk_bf16_f32 v91, v102, v103
	v_lshl_add_u64 v[92:93], v[92:93], 0, v[146:147]
	v_pk_mul_f32 v[86:87], v[86:87], v[100:101] op_sel_hi:[1,0]
	v_max_f32_e32 v84, 0, v84
	v_max_f32_e32 v80, 0, v80
	v_max_f32_e32 v85, 0, v85
	v_max_f32_e32 v81, 0, v81
	v_max_f32_e32 v82, 0, v82
	v_max_f32_e32 v83, 0, v83
	global_store_dwordx4 v[92:93], v[88:91], off
	v_pk_mul_f32 v[84:85], v[84:85], v[84:85]
	s_nop 0
	v_pk_mul_f32 v[88:89], v[80:81], v[80:81]
	v_max_f32_e32 v80, 0, v86
	v_max_f32_e32 v81, 0, v87
	v_pk_mul_f32 v[90:91], v[82:83], v[82:83]
	v_fmamk_f32 v83, v243, 0x3a800000, v164
	v_pk_mul_f32 v[86:87], v[80:81], v[80:81]
	v_cvt_pk_bf16_f32 v80, v84, v85
	v_rsq_f32_e32 v84, v83
	v_cvt_pk_bf16_f32 v81, v86, v87
	v_cvt_pk_bf16_f32 v82, v88, v89
	v_cvt_pk_bf16_f32 v83, v90, v91
	v_pk_mul_f32 v[76:77], v[76:77], v[84:85] op_sel_hi:[1,0]
	v_pk_mul_f32 v[72:73], v[72:73], v[84:85] op_sel_hi:[1,0]
	v_pk_mul_f32 v[78:79], v[78:79], v[84:85] op_sel_hi:[1,0]
	v_pk_mul_f32 v[74:75], v[74:75], v[84:85] op_sel_hi:[1,0]
	v_max_f32_e32 v76, 0, v76
	v_max_f32_e32 v72, 0, v72
	v_max_f32_e32 v77, 0, v77
	v_max_f32_e32 v73, 0, v73
	global_store_dwordx4 v[92:93], v[80:83], off offset:256
	v_pk_mul_f32 v[76:77], v[76:77], v[76:77]
	v_max_f32_e32 v74, 0, v74
	v_lshlrev_b64 v[80:81], 13, v[154:155]
	v_pk_mul_f32 v[82:83], v[72:73], v[72:73]
	v_max_f32_e32 v72, 0, v78
	v_max_f32_e32 v73, 0, v79
	v_max_f32_e32 v75, 0, v75
	v_pk_mul_f32 v[78:79], v[72:73], v[72:73]
	v_pk_mul_f32 v[86:87], v[74:75], v[74:75]
	v_cvt_pk_bf16_f32 v72, v76, v77
	v_lshl_add_u64 v[76:77], s[92:93], 0, v[80:81]
	v_pk_mul_f32 v[68:69], v[68:69], v[84:85] op_sel_hi:[1,0]
	v_pk_mul_f32 v[66:67], v[66:67], v[84:85] op_sel_hi:[1,0]
	v_pk_mul_f32 v[64:65], v[64:65], v[84:85] op_sel_hi:[1,0]
	v_cvt_pk_bf16_f32 v73, v78, v79
	v_cvt_pk_bf16_f32 v74, v82, v83
	v_cvt_pk_bf16_f32 v75, v86, v87
	v_lshl_add_u64 v[76:77], v[76:77], 0, v[146:147]
	v_pk_mul_f32 v[70:71], v[70:71], v[84:85] op_sel_hi:[1,0]
	v_max_f32_e32 v68, 0, v68
	v_max_f32_e32 v64, 0, v64
	v_max_f32_e32 v69, 0, v69
	v_max_f32_e32 v65, 0, v65
	v_max_f32_e32 v66, 0, v66
	v_max_f32_e32 v67, 0, v67
	global_store_dwordx4 v[76:77], v[72:75], off
	v_pk_mul_f32 v[68:69], v[68:69], v[68:69]
	s_nop 0
	v_pk_mul_f32 v[72:73], v[64:65], v[64:65]
	v_max_f32_e32 v64, 0, v70
	v_max_f32_e32 v65, 0, v71
	v_pk_mul_f32 v[74:75], v[66:67], v[66:67]
	v_fmamk_f32 v67, v244, 0x3a800000, v164
	v_pk_mul_f32 v[70:71], v[64:65], v[64:65]
	v_cvt_pk_bf16_f32 v64, v68, v69
	v_rsq_f32_e32 v68, v67
	v_cvt_pk_bf16_f32 v65, v70, v71
	v_cvt_pk_bf16_f32 v66, v72, v73
	v_cvt_pk_bf16_f32 v67, v74, v75
	v_pk_mul_f32 v[60:61], v[60:61], v[68:69] op_sel_hi:[1,0]
	v_pk_mul_f32 v[56:57], v[56:57], v[68:69] op_sel_hi:[1,0]
	v_pk_mul_f32 v[62:63], v[62:63], v[68:69] op_sel_hi:[1,0]
	v_pk_mul_f32 v[58:59], v[58:59], v[68:69] op_sel_hi:[1,0]
	v_max_f32_e32 v60, 0, v60
	v_max_f32_e32 v56, 0, v56
	v_max_f32_e32 v61, 0, v61
	v_max_f32_e32 v57, 0, v57
	global_store_dwordx4 v[76:77], v[64:67], off offset:256
	v_pk_mul_f32 v[60:61], v[60:61], v[60:61]
	v_max_f32_e32 v58, 0, v58
	v_lshlrev_b64 v[64:65], 13, v[152:153]
	v_pk_mul_f32 v[66:67], v[56:57], v[56:57]
	v_max_f32_e32 v56, 0, v62
	v_max_f32_e32 v57, 0, v63
	v_max_f32_e32 v59, 0, v59
	v_pk_mul_f32 v[62:63], v[56:57], v[56:57]
	v_pk_mul_f32 v[70:71], v[58:59], v[58:59]
	v_cvt_pk_bf16_f32 v56, v60, v61
	v_lshl_add_u64 v[60:61], s[92:93], 0, v[64:65]
	v_pk_mul_f32 v[52:53], v[52:53], v[68:69] op_sel_hi:[1,0]
	v_pk_mul_f32 v[50:51], v[50:51], v[68:69] op_sel_hi:[1,0]
	v_pk_mul_f32 v[48:49], v[48:49], v[68:69] op_sel_hi:[1,0]
	v_cvt_pk_bf16_f32 v57, v62, v63
	v_cvt_pk_bf16_f32 v58, v66, v67
	v_cvt_pk_bf16_f32 v59, v70, v71
	v_lshl_add_u64 v[60:61], v[60:61], 0, v[146:147]
	v_pk_mul_f32 v[54:55], v[54:55], v[68:69] op_sel_hi:[1,0]
	v_max_f32_e32 v52, 0, v52
	v_max_f32_e32 v48, 0, v48
	v_max_f32_e32 v53, 0, v53
	v_max_f32_e32 v49, 0, v49
	v_max_f32_e32 v50, 0, v50
	v_max_f32_e32 v51, 0, v51
	global_store_dwordx4 v[60:61], v[56:59], off
	v_pk_mul_f32 v[52:53], v[52:53], v[52:53]
	s_nop 0
	v_pk_mul_f32 v[56:57], v[48:49], v[48:49]
	v_max_f32_e32 v48, 0, v54
	v_max_f32_e32 v49, 0, v55
	v_pk_mul_f32 v[58:59], v[50:51], v[50:51]
	v_fmamk_f32 v51, v245, 0x3a800000, v164
	v_pk_mul_f32 v[54:55], v[48:49], v[48:49]
	v_cvt_pk_bf16_f32 v48, v52, v53
	v_rsq_f32_e32 v52, v51
	v_cvt_pk_bf16_f32 v49, v54, v55
	v_cvt_pk_bf16_f32 v50, v56, v57
	v_cvt_pk_bf16_f32 v51, v58, v59
	v_pk_mul_f32 v[44:45], v[44:45], v[52:53] op_sel_hi:[1,0]
	v_pk_mul_f32 v[40:41], v[40:41], v[52:53] op_sel_hi:[1,0]
	v_pk_mul_f32 v[46:47], v[46:47], v[52:53] op_sel_hi:[1,0]
	v_pk_mul_f32 v[42:43], v[42:43], v[52:53] op_sel_hi:[1,0]
	v_max_f32_e32 v44, 0, v44
	v_max_f32_e32 v40, 0, v40
	v_max_f32_e32 v45, 0, v45
	v_max_f32_e32 v41, 0, v41
	global_store_dwordx4 v[60:61], v[48:51], off offset:256
	v_pk_mul_f32 v[44:45], v[44:45], v[44:45]
	v_max_f32_e32 v42, 0, v42
	v_lshlrev_b64 v[48:49], 13, v[150:151]
	v_pk_mul_f32 v[50:51], v[40:41], v[40:41]
	v_max_f32_e32 v40, 0, v46
	v_max_f32_e32 v41, 0, v47
	v_max_f32_e32 v43, 0, v43
	v_pk_mul_f32 v[46:47], v[40:41], v[40:41]
	v_pk_mul_f32 v[54:55], v[42:43], v[42:43]
	v_cvt_pk_bf16_f32 v40, v44, v45
	v_lshl_add_u64 v[44:45], s[92:93], 0, v[48:49]
	v_pk_mul_f32 v[36:37], v[36:37], v[52:53] op_sel_hi:[1,0]
	v_pk_mul_f32 v[34:35], v[34:35], v[52:53] op_sel_hi:[1,0]
	v_pk_mul_f32 v[32:33], v[32:33], v[52:53] op_sel_hi:[1,0]
	v_cvt_pk_bf16_f32 v41, v46, v47
	v_cvt_pk_bf16_f32 v42, v50, v51
	v_cvt_pk_bf16_f32 v43, v54, v55
	v_lshl_add_u64 v[44:45], v[44:45], 0, v[146:147]
	v_pk_mul_f32 v[38:39], v[38:39], v[52:53] op_sel_hi:[1,0]
	v_max_f32_e32 v36, 0, v36
	v_max_f32_e32 v32, 0, v32
	v_max_f32_e32 v37, 0, v37
	v_max_f32_e32 v33, 0, v33
	v_max_f32_e32 v34, 0, v34
	v_max_f32_e32 v35, 0, v35
	global_store_dwordx4 v[44:45], v[40:43], off
	v_pk_mul_f32 v[36:37], v[36:37], v[36:37]
	s_nop 0
	v_pk_mul_f32 v[40:41], v[32:33], v[32:33]
	v_max_f32_e32 v32, 0, v38
	v_max_f32_e32 v33, 0, v39
	v_pk_mul_f32 v[42:43], v[34:35], v[34:35]
	v_fmamk_f32 v35, v246, 0x3a800000, v164
	v_pk_mul_f32 v[38:39], v[32:33], v[32:33]
	v_cvt_pk_bf16_f32 v32, v36, v37
	v_rsq_f32_e32 v36, v35
	v_cvt_pk_bf16_f32 v33, v38, v39
	v_cvt_pk_bf16_f32 v34, v40, v41
	v_cvt_pk_bf16_f32 v35, v42, v43
	v_pk_mul_f32 v[28:29], v[28:29], v[36:37] op_sel_hi:[1,0]
	v_pk_mul_f32 v[24:25], v[24:25], v[36:37] op_sel_hi:[1,0]
	v_pk_mul_f32 v[30:31], v[30:31], v[36:37] op_sel_hi:[1,0]
	v_pk_mul_f32 v[26:27], v[26:27], v[36:37] op_sel_hi:[1,0]
	v_max_f32_e32 v28, 0, v28
	v_max_f32_e32 v24, 0, v24
	v_max_f32_e32 v29, 0, v29
	v_max_f32_e32 v25, 0, v25
	global_store_dwordx4 v[44:45], v[32:35], off offset:256
	v_pk_mul_f32 v[28:29], v[28:29], v[28:29]
	v_max_f32_e32 v26, 0, v26
	v_lshlrev_b64 v[32:33], 13, v[148:149]
	v_pk_mul_f32 v[34:35], v[24:25], v[24:25]
	v_max_f32_e32 v24, 0, v30
	v_max_f32_e32 v25, 0, v31
	v_max_f32_e32 v27, 0, v27
	v_pk_mul_f32 v[30:31], v[24:25], v[24:25]
	v_pk_mul_f32 v[38:39], v[26:27], v[26:27]
	v_cvt_pk_bf16_f32 v24, v28, v29
	v_lshl_add_u64 v[28:29], s[92:93], 0, v[32:33]
	v_pk_mul_f32 v[20:21], v[20:21], v[36:37] op_sel_hi:[1,0]
	v_pk_mul_f32 v[18:19], v[18:19], v[36:37] op_sel_hi:[1,0]
	v_pk_mul_f32 v[16:17], v[16:17], v[36:37] op_sel_hi:[1,0]
	v_cvt_pk_bf16_f32 v25, v30, v31
	v_cvt_pk_bf16_f32 v26, v34, v35
	v_cvt_pk_bf16_f32 v27, v38, v39
	v_lshl_add_u64 v[28:29], v[28:29], 0, v[146:147]
	v_pk_mul_f32 v[22:23], v[22:23], v[36:37] op_sel_hi:[1,0]
	v_max_f32_e32 v20, 0, v20
	v_max_f32_e32 v16, 0, v16
	v_max_f32_e32 v21, 0, v21
	v_max_f32_e32 v17, 0, v17
	v_max_f32_e32 v18, 0, v18
	v_max_f32_e32 v19, 0, v19
	global_store_dwordx4 v[28:29], v[24:27], off
	v_pk_mul_f32 v[20:21], v[20:21], v[20:21]
	s_nop 0
	v_pk_mul_f32 v[24:25], v[16:17], v[16:17]
	v_max_f32_e32 v16, 0, v22
	v_max_f32_e32 v17, 0, v23
	v_pk_mul_f32 v[26:27], v[18:19], v[18:19]
	v_fmamk_f32 v19, v247, 0x3a800000, v164
	v_pk_mul_f32 v[22:23], v[16:17], v[16:17]
	v_cvt_pk_bf16_f32 v16, v20, v21
	v_rsq_f32_e32 v20, v19
	v_cvt_pk_bf16_f32 v17, v22, v23
	v_cvt_pk_bf16_f32 v18, v24, v25
	v_cvt_pk_bf16_f32 v19, v26, v27
	v_pk_mul_f32 v[12:13], v[12:13], v[20:21] op_sel_hi:[1,0]
	v_pk_mul_f32 v[8:9], v[8:9], v[20:21] op_sel_hi:[1,0]
	v_pk_mul_f32 v[14:15], v[14:15], v[20:21] op_sel_hi:[1,0]
	v_pk_mul_f32 v[10:11], v[10:11], v[20:21] op_sel_hi:[1,0]
	v_max_f32_e32 v12, 0, v12
	v_max_f32_e32 v8, 0, v8
	v_max_f32_e32 v13, 0, v13
	v_max_f32_e32 v9, 0, v9
	global_store_dwordx4 v[28:29], v[16:19], off offset:256
	v_pk_mul_f32 v[12:13], v[12:13], v[12:13]
	v_max_f32_e32 v10, 0, v10
	v_lshlrev_b64 v[16:17], 13, v[144:145]
	v_pk_mul_f32 v[18:19], v[8:9], v[8:9]
	v_max_f32_e32 v8, 0, v14
	v_max_f32_e32 v9, 0, v15
	v_max_f32_e32 v11, 0, v11
	v_pk_mul_f32 v[14:15], v[8:9], v[8:9]
	v_pk_mul_f32 v[22:23], v[10:11], v[10:11]
	v_cvt_pk_bf16_f32 v8, v12, v13
	v_lshl_add_u64 v[12:13], s[92:93], 0, v[16:17]
	v_pk_mul_f32 v[0:1], v[0:1], v[20:21] op_sel_hi:[1,0]
	v_cvt_pk_bf16_f32 v9, v14, v15
	v_cvt_pk_bf16_f32 v10, v18, v19
	v_cvt_pk_bf16_f32 v11, v22, v23
	v_lshl_add_u64 v[12:13], v[12:13], 0, v[146:147]
	v_pk_mul_f32 v[6:7], v[6:7], v[20:21] op_sel_hi:[1,0]
	v_pk_mul_f32 v[4:5], v[4:5], v[20:21] op_sel_hi:[1,0]
	v_pk_mul_f32 v[2:3], v[2:3], v[20:21] op_sel_hi:[1,0]
	v_max_f32_e32 v0, 0, v0
	v_max_f32_e32 v1, 0, v1
	global_store_dwordx4 v[12:13], v[8:11], off
	v_max_f32_e32 v4, 0, v4
	v_max_f32_e32 v5, 0, v5
	v_pk_mul_f32 v[8:9], v[0:1], v[0:1]
	v_max_f32_e32 v0, 0, v6
	v_max_f32_e32 v2, 0, v2
	v_max_f32_e32 v1, 0, v7
	v_max_f32_e32 v3, 0, v3
	v_pk_mul_f32 v[4:5], v[4:5], v[4:5]
	v_pk_mul_f32 v[6:7], v[0:1], v[0:1]
	v_pk_mul_f32 v[10:11], v[2:3], v[2:3]
	v_cvt_pk_bf16_f32 v0, v4, v5
	v_cvt_pk_bf16_f32 v1, v6, v7
	v_cvt_pk_bf16_f32 v2, v8, v9
	v_cvt_pk_bf16_f32 v3, v10, v11
	global_store_dwordx4 v[12:13], v[0:3], off offset:256
	s_cbranch_vccnz .LBB0_632
	s_andn2_b64 vcc, exec, s[4:5]
	s_cbranch_vccnz .LBB0_631
	s_barrier
	s_branch .LBB0_631

.LBB0_710:
	s_ashr_i32 s17, s16, 31
	s_lshl_b64 s[26:27], s[16:17], 21
	s_add_u32 s26, s92, s26
	s_addc_u32 s27, s93, s27
	s_and_b64 s[28:29], s[6:7], exec
	s_cselect_b32 s17, s27, s1
	s_cselect_b32 s33, s26, s0
	s_ashr_i32 s15, s14, 31
	s_lshl_b64 s[28:29], s[14:15], 21
	s_add_u32 s28, s56, s28
	s_addc_u32 s29, s57, s29
	s_and_b64 s[38:39], s[6:7], exec
	s_cselect_b32 s15, s29, s37
	s_cselect_b32 s55, s28, s36
	s_add_u32 s0, s0, 0x100080
	s_addc_u32 s1, s1, 0
	s_add_u32 s58, s36, 0x100
	s_addc_u32 s59, s37, 0
	s_mov_b32 s60, -2
	s_waitcnt lgkmcnt(0)
	ds_read_b128 v[128:131], v188
	ds_read_b128 v[132:135], v188 offset:1024
	ds_read_b128 v[136:139], v188 offset:2048
	ds_read_b128 v[140:143], v188 offset:3072
	ds_read_b128 v[144:147], v189
	ds_read_b128 v[148:151], v189 offset:1024
	ds_read_b128 v[152:155], v189 offset:2048
	ds_read_b128 v[156:159], v189 offset:3072
	s_add_u32 s36, s0, 0xfff00080
	s_addc_u32 s37, s1, -1
	s_cmp_eq_u32 s60, 60
	s_cselect_b32 s39, s17, s37
	s_cselect_b32 s38, s33, s36
	s_cselect_b32 s37, s15, s59
	s_cselect_b32 s36, s55, s58
	v_lshl_add_u64 v[220:221], s[0:1], 0, v[170:171]
	s_add_i32 m0, s31, 0xc000
	ds_read_b128 v[178:181], v190
	ds_read_b128 v[192:195], v190 offset:1024
	ds_read_b128 v[196:199], v190 offset:2048
	ds_read_b128 v[200:203], v190 offset:3072
	ds_read_b128 v[204:207], v190 offset:4096
	ds_read_b128 v[208:211], v190 offset:5120
	ds_read_b128 v[212:215], v190 offset:6144
	ds_read_b128 v[216:219], v190 offset:7168
	global_load_lds_dwordx4 v[220:221], off
	v_lshl_add_u64 v[220:221], s[0:1], 0, v[172:173]
	s_add_i32 m0, s31, 0xe000
	s_nop 0
	global_load_lds_dwordx4 v[220:221], off
	s_waitcnt vmcnt(8)
	s_waitcnt lgkmcnt(0)
	s_barrier
	s_setprio 1
	s_waitcnt lgkmcnt(0)
	v_mfma_f32_16x16x32_bf16 v[124:127], v[128:131], v[178:181], 0
	v_mfma_f32_16x16x32_bf16 v[120:123], v[136:139], v[178:181], 0
	v_mfma_f32_16x16x32_bf16 v[108:111], v[128:131], v[196:199], 0
	v_mfma_f32_16x16x32_bf16 v[104:107], v[136:139], v[196:199], 0
	v_mfma_f32_16x16x32_bf16 v[92:95], v[128:131], v[204:207], 0
	v_mfma_f32_16x16x32_bf16 v[88:91], v[136:139], v[204:207], 0
	v_mfma_f32_16x16x32_bf16 v[76:79], v[128:131], v[212:215], 0
	v_mfma_f32_16x16x32_bf16 v[72:75], v[136:139], v[212:215], 0
	v_mfma_f32_16x16x32_bf16 v[124:127], v[132:135], v[192:195], v[124:127]
	v_mfma_f32_16x16x32_bf16 v[120:123], v[140:143], v[192:195], v[120:123]
	v_mfma_f32_16x16x32_bf16 v[108:111], v[132:135], v[200:203], v[108:111]
	v_mfma_f32_16x16x32_bf16 v[104:107], v[140:143], v[200:203], v[104:107]
	v_mfma_f32_16x16x32_bf16 v[92:95], v[132:135], v[208:211], v[92:95]
	v_mfma_f32_16x16x32_bf16 v[88:91], v[140:143], v[208:211], v[88:91]
	v_mfma_f32_16x16x32_bf16 v[76:79], v[132:135], v[216:219], v[76:79]
	v_mfma_f32_16x16x32_bf16 v[72:75], v[140:143], v[216:219], v[72:75]
	s_setprio 0
	s_setprio 1
	v_mfma_f32_16x16x32_bf16 v[116:119], v[144:147], v[178:181], 0
	v_mfma_f32_16x16x32_bf16 v[112:115], v[152:155], v[178:181], 0
	v_mfma_f32_16x16x32_bf16 v[100:103], v[144:147], v[196:199], 0
	v_mfma_f32_16x16x32_bf16 v[96:99], v[152:155], v[196:199], 0
	v_mfma_f32_16x16x32_bf16 v[84:87], v[144:147], v[204:207], 0
	v_mfma_f32_16x16x32_bf16 v[80:83], v[152:155], v[204:207], 0
	v_mfma_f32_16x16x32_bf16 v[68:71], v[144:147], v[212:215], 0
	v_mfma_f32_16x16x32_bf16 v[64:67], v[152:155], v[212:215], 0
	v_mfma_f32_16x16x32_bf16 v[116:119], v[148:151], v[192:195], v[116:119]
	v_mfma_f32_16x16x32_bf16 v[112:115], v[156:159], v[192:195], v[112:115]
	v_mfma_f32_16x16x32_bf16 v[100:103], v[148:151], v[200:203], v[100:103]
	v_mfma_f32_16x16x32_bf16 v[96:99], v[156:159], v[200:203], v[96:99]
	v_mfma_f32_16x16x32_bf16 v[84:87], v[148:151], v[208:211], v[84:87]
	v_mfma_f32_16x16x32_bf16 v[80:83], v[156:159], v[208:211], v[80:83]
	v_mfma_f32_16x16x32_bf16 v[68:71], v[148:151], v[216:219], v[68:71]
	v_mfma_f32_16x16x32_bf16 v[64:67], v[156:159], v[216:219], v[64:67]
	s_setprio 0
	s_barrier
	s_add_i32 s61, s49, s40
	v_lshl_add_u64 v[220:221], s[36:37], 0, v[164:165]
	s_mov_b32 m0, s61
	ds_read_b128 v[178:181], v190 offset:16384
	ds_read_b128 v[192:195], v190 offset:17408
	ds_read_b128 v[196:199], v190 offset:18432
	ds_read_b128 v[200:203], v190 offset:19456
	ds_read_b128 v[204:207], v190 offset:20480
	ds_read_b128 v[208:211], v190 offset:21504
	ds_read_b128 v[212:215], v190 offset:22528
	ds_read_b128 v[216:219], v190 offset:23552
	global_load_lds_dwordx4 v[220:221], off
	s_add_i32 m0, s61, 0x2000
	s_add_u32 s62, s36, 0x100000
	v_lshl_add_u64 v[222:223], s[36:37], 0, v[168:169]
	s_addc_u32 s63, s37, 0
	s_add_i32 s61, s50, s40
	global_load_lds_dwordx4 v[222:223], off
	v_lshl_add_u64 v[224:225], s[62:63], 0, v[164:165]
	s_mov_b32 m0, s61
	v_lshl_add_u64 v[226:227], s[38:39], 0, v[166:167]
	global_load_lds_dwordx4 v[224:225], off
	v_lshl_add_u64 v[224:225], s[62:63], 0, v[168:169]
	s_add_i32 m0, s61, 0x2000
	s_nop 0
	global_load_lds_dwordx4 v[224:225], off
	v_lshl_add_u64 v[224:225], s[38:39], 0, v[162:163]
	s_mov_b32 m0, s31
	s_nop 0
	global_load_lds_dwordx4 v[224:225], off
	s_mov_b32 m0, s35
	s_nop 0
	global_load_lds_dwordx4 v[226:227], off
	s_waitcnt vmcnt(8)
	s_waitcnt lgkmcnt(0)
	s_barrier
	s_setprio 1
	s_waitcnt lgkmcnt(0)
	v_mfma_f32_16x16x32_bf16 v[60:63], v[128:131], v[178:181], 0
	v_mfma_f32_16x16x32_bf16 v[56:59], v[136:139], v[178:181], 0
	v_mfma_f32_16x16x32_bf16 v[44:47], v[128:131], v[196:199], 0
	v_mfma_f32_16x16x32_bf16 v[40:43], v[136:139], v[196:199], 0
	v_mfma_f32_16x16x32_bf16 v[28:31], v[128:131], v[204:207], 0
	v_mfma_f32_16x16x32_bf16 v[24:27], v[136:139], v[204:207], 0
	v_mfma_f32_16x16x32_bf16 v[12:15], v[128:131], v[212:215], 0
	v_mfma_f32_16x16x32_bf16 v[8:11], v[136:139], v[212:215], 0
	v_mfma_f32_16x16x32_bf16 v[60:63], v[132:135], v[192:195], v[60:63]
	v_mfma_f32_16x16x32_bf16 v[56:59], v[140:143], v[192:195], v[56:59]
	v_mfma_f32_16x16x32_bf16 v[44:47], v[132:135], v[200:203], v[44:47]
	v_mfma_f32_16x16x32_bf16 v[40:43], v[140:143], v[200:203], v[40:43]
	v_mfma_f32_16x16x32_bf16 v[28:31], v[132:135], v[208:211], v[28:31]
	v_mfma_f32_16x16x32_bf16 v[24:27], v[140:143], v[208:211], v[24:27]
	v_mfma_f32_16x16x32_bf16 v[12:15], v[132:135], v[216:219], v[12:15]
	v_mfma_f32_16x16x32_bf16 v[8:11], v[140:143], v[216:219], v[8:11]
	s_setprio 0
	s_setprio 1
	v_mfma_f32_16x16x32_bf16 v[52:55], v[144:147], v[178:181], 0
	v_mfma_f32_16x16x32_bf16 v[48:51], v[152:155], v[178:181], 0
	v_mfma_f32_16x16x32_bf16 v[36:39], v[144:147], v[196:199], 0
	v_mfma_f32_16x16x32_bf16 v[32:35], v[152:155], v[196:199], 0
	v_mfma_f32_16x16x32_bf16 v[20:23], v[144:147], v[204:207], 0
	v_mfma_f32_16x16x32_bf16 v[16:19], v[152:155], v[204:207], 0
	v_mfma_f32_16x16x32_bf16 v[4:7], v[144:147], v[212:215], 0
	v_mfma_f32_16x16x32_bf16 v[0:3], v[152:155], v[212:215], 0
	v_mfma_f32_16x16x32_bf16 v[52:55], v[148:151], v[192:195], v[52:55]
	v_mfma_f32_16x16x32_bf16 v[48:51], v[156:159], v[192:195], v[48:51]
	v_mfma_f32_16x16x32_bf16 v[36:39], v[148:151], v[200:203], v[36:39]
	v_mfma_f32_16x16x32_bf16 v[32:35], v[156:159], v[200:203], v[32:35]
	v_mfma_f32_16x16x32_bf16 v[20:23], v[148:151], v[208:211], v[20:23]
	v_mfma_f32_16x16x32_bf16 v[16:19], v[156:159], v[208:211], v[16:19]
	v_mfma_f32_16x16x32_bf16 v[4:7], v[148:151], v[216:219], v[4:7]
	v_mfma_f32_16x16x32_bf16 v[0:3], v[156:159], v[216:219], v[0:3]
	s_setprio 0
	s_barrier
	s_add_i32 s61, 0, 0x18000
	s_add_i32 s62, 0, 0x1c000
	v_add_u32_e32 v140, s61, v183
	v_add_u32_e32 v156, s62, v183
	ds_read_b128 v[128:131], v140
	ds_read_b128 v[132:135], v140 offset:1024
	ds_read_b128 v[136:139], v140 offset:2048
	ds_read_b128 v[140:143], v140 offset:3072
	ds_read_b128 v[144:147], v156
	ds_read_b128 v[148:151], v156 offset:1024
	ds_read_b128 v[152:155], v156 offset:2048
	ds_read_b128 v[156:159], v156 offset:3072
	s_add_u32 s38, s38, 0x100000
	s_addc_u32 s39, s39, 0
	s_mov_b32 m0, s41
	v_lshl_add_u64 v[228:229], s[38:39], 0, v[162:163]
	ds_read_b128 v[178:181], v190 offset:32768
	ds_read_b128 v[192:195], v190 offset:33792
	ds_read_b128 v[196:199], v190 offset:34816
	ds_read_b128 v[200:203], v190 offset:35840
	ds_read_b128 v[204:207], v190 offset:36864
	ds_read_b128 v[208:211], v190 offset:37888
	ds_read_b128 v[212:215], v190 offset:38912
	ds_read_b128 v[216:219], v190 offset:39936
	global_load_lds_dwordx4 v[228:229], off
	v_lshl_add_u64 v[228:229], s[38:39], 0, v[166:167]
	s_mov_b32 m0, s42
	s_nop 0
	global_load_lds_dwordx4 v[228:229], off
	s_waitcnt vmcnt(8)
	s_waitcnt lgkmcnt(0)
	s_barrier
	s_setprio 1
	s_waitcnt lgkmcnt(0)
	v_mfma_f32_16x16x32_bf16 v[124:127], v[128:131], v[178:181], v[124:127]
	v_mfma_f32_16x16x32_bf16 v[120:123], v[136:139], v[178:181], v[120:123]
	v_mfma_f32_16x16x32_bf16 v[108:111], v[128:131], v[196:199], v[108:111]
	v_mfma_f32_16x16x32_bf16 v[104:107], v[136:139], v[196:199], v[104:107]
	v_mfma_f32_16x16x32_bf16 v[92:95], v[128:131], v[204:207], v[92:95]
	v_mfma_f32_16x16x32_bf16 v[88:91], v[136:139], v[204:207], v[88:91]
	v_mfma_f32_16x16x32_bf16 v[76:79], v[128:131], v[212:215], v[76:79]
	v_mfma_f32_16x16x32_bf16 v[72:75], v[136:139], v[212:215], v[72:75]
	v_mfma_f32_16x16x32_bf16 v[124:127], v[132:135], v[192:195], v[124:127]
	v_mfma_f32_16x16x32_bf16 v[120:123], v[140:143], v[192:195], v[120:123]
	v_mfma_f32_16x16x32_bf16 v[108:111], v[132:135], v[200:203], v[108:111]
	v_mfma_f32_16x16x32_bf16 v[104:107], v[140:143], v[200:203], v[104:107]
	v_mfma_f32_16x16x32_bf16 v[92:95], v[132:135], v[208:211], v[92:95]
	v_mfma_f32_16x16x32_bf16 v[88:91], v[140:143], v[208:211], v[88:91]
	v_mfma_f32_16x16x32_bf16 v[76:79], v[132:135], v[216:219], v[76:79]
	v_mfma_f32_16x16x32_bf16 v[72:75], v[140:143], v[216:219], v[72:75]
	s_setprio 0
	s_setprio 1
	v_mfma_f32_16x16x32_bf16 v[116:119], v[144:147], v[178:181], v[116:119]
	v_mfma_f32_16x16x32_bf16 v[112:115], v[152:155], v[178:181], v[112:115]
	v_mfma_f32_16x16x32_bf16 v[100:103], v[144:147], v[196:199], v[100:103]
	v_mfma_f32_16x16x32_bf16 v[96:99], v[152:155], v[196:199], v[96:99]
	v_mfma_f32_16x16x32_bf16 v[84:87], v[144:147], v[204:207], v[84:87]
	v_mfma_f32_16x16x32_bf16 v[80:83], v[152:155], v[204:207], v[80:83]
	v_mfma_f32_16x16x32_bf16 v[68:71], v[144:147], v[212:215], v[68:71]
	v_mfma_f32_16x16x32_bf16 v[64:67], v[152:155], v[212:215], v[64:67]
	v_mfma_f32_16x16x32_bf16 v[116:119], v[148:151], v[192:195], v[116:119]
	v_mfma_f32_16x16x32_bf16 v[112:115], v[156:159], v[192:195], v[112:115]
	v_mfma_f32_16x16x32_bf16 v[100:103], v[148:151], v[200:203], v[100:103]
	v_mfma_f32_16x16x32_bf16 v[96:99], v[156:159], v[200:203], v[96:99]
	v_mfma_f32_16x16x32_bf16 v[84:87], v[148:151], v[208:211], v[84:87]
	v_mfma_f32_16x16x32_bf16 v[80:83], v[156:159], v[208:211], v[80:83]
	v_mfma_f32_16x16x32_bf16 v[68:71], v[148:151], v[216:219], v[68:71]
	v_mfma_f32_16x16x32_bf16 v[64:67], v[156:159], v[216:219], v[64:67]
	s_setprio 0
	s_barrier
	s_add_i32 s38, s61, s40
	v_lshl_add_u64 v[220:221], v[220:221], 0, s[8:9]
	s_mov_b32 m0, s38
	ds_read_b128 v[178:181], v190 offset:49152
	ds_read_b128 v[192:195], v190 offset:50176
	ds_read_b128 v[196:199], v190 offset:51200
	ds_read_b128 v[200:203], v190 offset:52224
	ds_read_b128 v[204:207], v190 offset:53248
	ds_read_b128 v[208:211], v190 offset:54272
	ds_read_b128 v[212:215], v190 offset:55296
	ds_read_b128 v[216:219], v190 offset:56320
	global_load_lds_dwordx4 v[220:221], off
	s_add_i32 m0, s38, 0x2000
	s_add_u32 s36, s36, 0x100080
	v_lshl_add_u64 v[220:221], v[222:223], 0, s[8:9]
	s_addc_u32 s37, s37, 0
	s_add_i32 s38, s62, s40
	global_load_lds_dwordx4 v[220:221], off
	v_lshl_add_u64 v[220:221], s[36:37], 0, v[164:165]
	s_mov_b32 m0, s38
	s_nop 0
	global_load_lds_dwordx4 v[220:221], off
	v_lshl_add_u64 v[220:221], s[36:37], 0, v[168:169]
	s_add_i32 m0, s38, 0x2000
	s_nop 0
	global_load_lds_dwordx4 v[220:221], off
	v_lshl_add_u64 v[220:221], v[224:225], 0, s[8:9]
	s_mov_b32 m0, s45
	s_nop 0
	global_load_lds_dwordx4 v[220:221], off
	v_lshl_add_u64 v[220:221], v[226:227], 0, s[8:9]
	s_mov_b32 m0, s46
	s_nop 0
	global_load_lds_dwordx4 v[220:221], off
	s_waitcnt vmcnt(8)
	s_waitcnt lgkmcnt(0)
	s_barrier
	s_setprio 1
	s_waitcnt lgkmcnt(0)
	v_mfma_f32_16x16x32_bf16 v[60:63], v[128:131], v[178:181], v[60:63]
	v_mfma_f32_16x16x32_bf16 v[56:59], v[136:139], v[178:181], v[56:59]
	v_mfma_f32_16x16x32_bf16 v[44:47], v[128:131], v[196:199], v[44:47]
	v_mfma_f32_16x16x32_bf16 v[40:43], v[136:139], v[196:199], v[40:43]
	v_mfma_f32_16x16x32_bf16 v[28:31], v[128:131], v[204:207], v[28:31]
	v_mfma_f32_16x16x32_bf16 v[24:27], v[136:139], v[204:207], v[24:27]
	v_mfma_f32_16x16x32_bf16 v[12:15], v[128:131], v[212:215], v[12:15]
	v_mfma_f32_16x16x32_bf16 v[8:11], v[136:139], v[212:215], v[8:11]
	v_mfma_f32_16x16x32_bf16 v[60:63], v[132:135], v[192:195], v[60:63]
	v_mfma_f32_16x16x32_bf16 v[56:59], v[140:143], v[192:195], v[56:59]
	v_mfma_f32_16x16x32_bf16 v[44:47], v[132:135], v[200:203], v[44:47]
	v_mfma_f32_16x16x32_bf16 v[40:43], v[140:143], v[200:203], v[40:43]
	v_mfma_f32_16x16x32_bf16 v[28:31], v[132:135], v[208:211], v[28:31]
	v_mfma_f32_16x16x32_bf16 v[24:27], v[140:143], v[208:211], v[24:27]
	v_mfma_f32_16x16x32_bf16 v[12:15], v[132:135], v[216:219], v[12:15]
	v_mfma_f32_16x16x32_bf16 v[8:11], v[140:143], v[216:219], v[8:11]
	s_setprio 0
	s_setprio 1
	v_mfma_f32_16x16x32_bf16 v[52:55], v[144:147], v[178:181], v[52:55]
	v_mfma_f32_16x16x32_bf16 v[48:51], v[152:155], v[178:181], v[48:51]
	v_mfma_f32_16x16x32_bf16 v[36:39], v[144:147], v[196:199], v[36:39]
	v_mfma_f32_16x16x32_bf16 v[32:35], v[152:155], v[196:199], v[32:35]
	v_mfma_f32_16x16x32_bf16 v[20:23], v[144:147], v[204:207], v[20:23]
	v_mfma_f32_16x16x32_bf16 v[16:19], v[152:155], v[204:207], v[16:19]
	v_mfma_f32_16x16x32_bf16 v[4:7], v[144:147], v[212:215], v[4:7]
	v_mfma_f32_16x16x32_bf16 v[0:3], v[152:155], v[212:215], v[0:3]
	v_mfma_f32_16x16x32_bf16 v[52:55], v[148:151], v[192:195], v[52:55]
	v_mfma_f32_16x16x32_bf16 v[48:51], v[156:159], v[192:195], v[48:51]
	v_mfma_f32_16x16x32_bf16 v[36:39], v[148:151], v[200:203], v[36:39]
	v_mfma_f32_16x16x32_bf16 v[32:35], v[156:159], v[200:203], v[32:35]
	v_mfma_f32_16x16x32_bf16 v[20:23], v[148:151], v[208:211], v[20:23]
	v_mfma_f32_16x16x32_bf16 v[16:19], v[156:159], v[208:211], v[16:19]
	v_mfma_f32_16x16x32_bf16 v[4:7], v[148:151], v[216:219], v[4:7]
	v_mfma_f32_16x16x32_bf16 v[0:3], v[156:159], v[216:219], v[0:3]
	s_setprio 0
	s_barrier
	s_add_i32 s60, s60, 2
	s_add_u32 s0, s0, 0x100
	s_addc_u32 s1, s1, 0
	s_add_u32 s58, s58, 0x100
	s_addc_u32 s59, s59, 0
	s_cmp_gt_u32 s60, 61
	s_cbranch_scc0 .LBB0_711
	s_branch .Lpeel_exit_4

.LBB0_798:
	s_ashr_i32 s29, s28, 31
	s_lshl_b64 s[30:31], s[28:29], 19
	s_add_u32 s30, s96, s30
	s_addc_u32 s31, s97, s31
	s_and_b64 s[34:35], s[4:5], exec
	s_cselect_b32 s3, s31, s1
	s_cselect_b32 s7, s30, s0
	s_ashr_i32 s27, s26, 31
	s_lshl_b64 s[34:35], s[26:27], 19
	s_add_u32 s34, s58, s34
	s_addc_u32 s35, s59, s35
	s_and_b64 s[36:37], s[4:5], exec
	s_cselect_b32 s27, s35, s9
	s_cselect_b32 s29, s34, s8
	s_add_u32 s0, s0, 0x40080
	s_addc_u32 s1, s1, 0
	s_add_u32 s33, s8, 0x100
	s_addc_u32 s38, s9, 0
	s_mov_b32 s39, -2
	ds_read_b128 v[128:131], v177
	ds_read_b128 v[154:157], v177 offset:1024
	ds_read_b128 v[162:165], v177 offset:2048
	ds_read_b128 v[166:169], v177 offset:3072
	ds_read_b128 v[182:185], v178
	ds_read_b128 v[186:189], v178 offset:1024
	ds_read_b128 v[190:193], v178 offset:2048
	ds_read_b128 v[194:197], v178 offset:3072
	s_add_u32 s8, s0, 0xfffc0080
	s_addc_u32 s9, s1, -1
	s_cmp_eq_u32 s39, 12
	s_cselect_b32 s37, s3, s9
	s_cselect_b32 s36, s7, s8
	s_cselect_b32 s9, s27, s38
	s_cselect_b32 s8, s29, s33
	v_lshl_add_u64 v[158:159], s[0:1], 0, v[146:147]
	s_add_i32 m0, s62, 0xc000
	ds_read_b128 v[198:201], v179
	ds_read_b128 v[202:205], v179 offset:1024
	ds_read_b128 v[206:209], v179 offset:2048
	ds_read_b128 v[210:213], v179 offset:3072
	ds_read_b128 v[214:217], v179 offset:4096
	ds_read_b128 v[218:221], v179 offset:5120
	ds_read_b128 v[222:225], v179 offset:6144
	ds_read_b128 v[226:229], v179 offset:7168
	global_load_lds_dwordx4 v[158:159], off
	v_lshl_add_u64 v[158:159], s[0:1], 0, v[148:149]
	s_add_i32 m0, s62, 0xe000
	s_nop 0
	global_load_lds_dwordx4 v[158:159], off
	s_waitcnt vmcnt(8)
	s_waitcnt lgkmcnt(0)
	s_barrier
	s_setprio 1
	s_waitcnt lgkmcnt(0)
	v_mfma_f32_16x16x32_bf16 v[124:127], v[128:131], v[198:201], 0
	v_mfma_f32_16x16x32_bf16 v[120:123], v[162:165], v[198:201], 0
	v_mfma_f32_16x16x32_bf16 v[108:111], v[128:131], v[206:209], 0
	v_mfma_f32_16x16x32_bf16 v[104:107], v[162:165], v[206:209], 0
	v_mfma_f32_16x16x32_bf16 v[92:95], v[128:131], v[214:217], 0
	v_mfma_f32_16x16x32_bf16 v[88:91], v[162:165], v[214:217], 0
	v_mfma_f32_16x16x32_bf16 v[76:79], v[128:131], v[222:225], 0
	v_mfma_f32_16x16x32_bf16 v[72:75], v[162:165], v[222:225], 0
	v_mfma_f32_16x16x32_bf16 v[124:127], v[154:157], v[202:205], v[124:127]
	v_mfma_f32_16x16x32_bf16 v[120:123], v[166:169], v[202:205], v[120:123]
	v_mfma_f32_16x16x32_bf16 v[108:111], v[154:157], v[210:213], v[108:111]
	v_mfma_f32_16x16x32_bf16 v[104:107], v[166:169], v[210:213], v[104:107]
	v_mfma_f32_16x16x32_bf16 v[92:95], v[154:157], v[218:221], v[92:95]
	v_mfma_f32_16x16x32_bf16 v[88:91], v[166:169], v[218:221], v[88:91]
	v_mfma_f32_16x16x32_bf16 v[76:79], v[154:157], v[226:229], v[76:79]
	v_mfma_f32_16x16x32_bf16 v[72:75], v[166:169], v[226:229], v[72:75]
	s_setprio 0
	s_setprio 1
	v_mfma_f32_16x16x32_bf16 v[116:119], v[182:185], v[198:201], 0
	v_mfma_f32_16x16x32_bf16 v[112:115], v[190:193], v[198:201], 0
	v_mfma_f32_16x16x32_bf16 v[100:103], v[182:185], v[206:209], 0
	v_mfma_f32_16x16x32_bf16 v[96:99], v[190:193], v[206:209], 0
	v_mfma_f32_16x16x32_bf16 v[84:87], v[182:185], v[214:217], 0
	v_mfma_f32_16x16x32_bf16 v[80:83], v[190:193], v[214:217], 0
	v_mfma_f32_16x16x32_bf16 v[68:71], v[182:185], v[222:225], 0
	v_mfma_f32_16x16x32_bf16 v[64:67], v[190:193], v[222:225], 0
	v_mfma_f32_16x16x32_bf16 v[116:119], v[186:189], v[202:205], v[116:119]
	v_mfma_f32_16x16x32_bf16 v[112:115], v[194:197], v[202:205], v[112:115]
	v_mfma_f32_16x16x32_bf16 v[100:103], v[186:189], v[210:213], v[100:103]
	v_mfma_f32_16x16x32_bf16 v[96:99], v[194:197], v[210:213], v[96:99]
	v_mfma_f32_16x16x32_bf16 v[84:87], v[186:189], v[218:221], v[84:87]
	v_mfma_f32_16x16x32_bf16 v[80:83], v[194:197], v[218:221], v[80:83]
	v_mfma_f32_16x16x32_bf16 v[68:71], v[186:189], v[226:229], v[68:71]
	v_mfma_f32_16x16x32_bf16 v[64:67], v[194:197], v[226:229], v[64:67]
	s_setprio 0
	s_barrier
	s_add_i32 s40, s78, s61
	v_lshl_add_u64 v[158:159], s[8:9], 0, v[134:135]
	s_mov_b32 m0, s40
	ds_read_b128 v[198:201], v179 offset:16384
	ds_read_b128 v[202:205], v179 offset:17408
	ds_read_b128 v[206:209], v179 offset:18432
	ds_read_b128 v[210:213], v179 offset:19456
	ds_read_b128 v[214:217], v179 offset:20480
	ds_read_b128 v[218:221], v179 offset:21504
	ds_read_b128 v[222:225], v179 offset:22528
	ds_read_b128 v[226:229], v179 offset:23552
	global_load_lds_dwordx4 v[158:159], off
	s_add_i32 m0, s40, 0x2000
	s_add_u32 s40, s8, 0x40000
	v_lshl_add_u64 v[230:231], s[8:9], 0, v[138:139]
	s_addc_u32 s41, s9, 0
	s_add_i32 s42, s79, s61
	global_load_lds_dwordx4 v[230:231], off
	v_lshl_add_u64 v[232:233], s[40:41], 0, v[134:135]
	s_mov_b32 m0, s42
	v_lshl_add_u64 v[234:235], s[36:37], 0, v[136:137]
	global_load_lds_dwordx4 v[232:233], off
	v_lshl_add_u64 v[232:233], s[40:41], 0, v[138:139]
	s_add_i32 m0, s42, 0x2000
	s_nop 0
	global_load_lds_dwordx4 v[232:233], off
	v_lshl_add_u64 v[232:233], s[36:37], 0, v[132:133]
	s_mov_b32 m0, s62
	s_nop 0
	global_load_lds_dwordx4 v[232:233], off
	s_mov_b32 m0, s63
	s_nop 0
	global_load_lds_dwordx4 v[234:235], off
	s_waitcnt vmcnt(8)
	s_waitcnt lgkmcnt(0)
	s_barrier
	s_setprio 1
	s_waitcnt lgkmcnt(0)
	v_mfma_f32_16x16x32_bf16 v[60:63], v[128:131], v[198:201], 0
	v_mfma_f32_16x16x32_bf16 v[56:59], v[162:165], v[198:201], 0
	v_mfma_f32_16x16x32_bf16 v[44:47], v[128:131], v[206:209], 0
	v_mfma_f32_16x16x32_bf16 v[40:43], v[162:165], v[206:209], 0
	v_mfma_f32_16x16x32_bf16 v[28:31], v[128:131], v[214:217], 0
	v_mfma_f32_16x16x32_bf16 v[24:27], v[162:165], v[214:217], 0
	v_mfma_f32_16x16x32_bf16 v[12:15], v[128:131], v[222:225], 0
	v_mfma_f32_16x16x32_bf16 v[8:11], v[162:165], v[222:225], 0
	v_mfma_f32_16x16x32_bf16 v[60:63], v[154:157], v[202:205], v[60:63]
	v_mfma_f32_16x16x32_bf16 v[56:59], v[166:169], v[202:205], v[56:59]
	v_mfma_f32_16x16x32_bf16 v[44:47], v[154:157], v[210:213], v[44:47]
	v_mfma_f32_16x16x32_bf16 v[40:43], v[166:169], v[210:213], v[40:43]
	v_mfma_f32_16x16x32_bf16 v[28:31], v[154:157], v[218:221], v[28:31]
	v_mfma_f32_16x16x32_bf16 v[24:27], v[166:169], v[218:221], v[24:27]
	v_mfma_f32_16x16x32_bf16 v[12:15], v[154:157], v[226:229], v[12:15]
	v_mfma_f32_16x16x32_bf16 v[8:11], v[166:169], v[226:229], v[8:11]
	s_setprio 0
	s_setprio 1
	v_mfma_f32_16x16x32_bf16 v[52:55], v[182:185], v[198:201], 0
	v_mfma_f32_16x16x32_bf16 v[48:51], v[190:193], v[198:201], 0
	v_mfma_f32_16x16x32_bf16 v[36:39], v[182:185], v[206:209], 0
	v_mfma_f32_16x16x32_bf16 v[32:35], v[190:193], v[206:209], 0
	v_mfma_f32_16x16x32_bf16 v[20:23], v[182:185], v[214:217], 0
	v_mfma_f32_16x16x32_bf16 v[16:19], v[190:193], v[214:217], 0
	v_mfma_f32_16x16x32_bf16 v[4:7], v[182:185], v[222:225], 0
	v_mfma_f32_16x16x32_bf16 v[0:3], v[190:193], v[222:225], 0
	v_mfma_f32_16x16x32_bf16 v[52:55], v[186:189], v[202:205], v[52:55]
	v_mfma_f32_16x16x32_bf16 v[48:51], v[194:197], v[202:205], v[48:51]
	v_mfma_f32_16x16x32_bf16 v[36:39], v[186:189], v[210:213], v[36:39]
	v_mfma_f32_16x16x32_bf16 v[32:35], v[194:197], v[210:213], v[32:35]
	v_mfma_f32_16x16x32_bf16 v[20:23], v[186:189], v[218:221], v[20:23]
	v_mfma_f32_16x16x32_bf16 v[16:19], v[194:197], v[218:221], v[16:19]
	v_mfma_f32_16x16x32_bf16 v[4:7], v[186:189], v[226:229], v[4:7]
	v_mfma_f32_16x16x32_bf16 v[0:3], v[194:197], v[226:229], v[0:3]
	s_setprio 0
	s_barrier
	s_add_i32 s40, 0, 0x18000
	v_add_u32_e32 v140, s40, v171
	s_add_i32 s41, 0, 0x1c000
	ds_read_b128 v[128:131], v140
	ds_read_b128 v[154:157], v140 offset:1024
	ds_read_b128 v[162:165], v140 offset:2048
	ds_read_b128 v[166:169], v140 offset:3072
	v_add_u32_e32 v140, s41, v171
	ds_read_b128 v[182:185], v140
	ds_read_b128 v[186:189], v140 offset:1024
	ds_read_b128 v[190:193], v140 offset:2048
	ds_read_b128 v[194:197], v140 offset:3072
	s_add_u32 s36, s36, 0x40000
	s_addc_u32 s37, s37, 0
	s_mov_b32 m0, s64
	v_lshl_add_u64 v[236:237], s[36:37], 0, v[132:133]
	ds_read_b128 v[198:201], v179 offset:32768
	ds_read_b128 v[202:205], v179 offset:33792
	ds_read_b128 v[206:209], v179 offset:34816
	ds_read_b128 v[210:213], v179 offset:35840
	ds_read_b128 v[214:217], v179 offset:36864
	ds_read_b128 v[218:221], v179 offset:37888
	ds_read_b128 v[222:225], v179 offset:38912
	ds_read_b128 v[226:229], v179 offset:39936
	global_load_lds_dwordx4 v[236:237], off
	v_lshl_add_u64 v[236:237], s[36:37], 0, v[136:137]
	s_mov_b32 m0, s65
	s_nop 0
	global_load_lds_dwordx4 v[236:237], off
	s_waitcnt vmcnt(8)
	s_waitcnt lgkmcnt(0)
	s_barrier
	s_setprio 1
	s_waitcnt lgkmcnt(0)
	v_mfma_f32_16x16x32_bf16 v[124:127], v[128:131], v[198:201], v[124:127]
	v_mfma_f32_16x16x32_bf16 v[120:123], v[162:165], v[198:201], v[120:123]
	v_mfma_f32_16x16x32_bf16 v[108:111], v[128:131], v[206:209], v[108:111]
	v_mfma_f32_16x16x32_bf16 v[104:107], v[162:165], v[206:209], v[104:107]
	v_mfma_f32_16x16x32_bf16 v[92:95], v[128:131], v[214:217], v[92:95]
	v_mfma_f32_16x16x32_bf16 v[88:91], v[162:165], v[214:217], v[88:91]
	v_mfma_f32_16x16x32_bf16 v[76:79], v[128:131], v[222:225], v[76:79]
	v_mfma_f32_16x16x32_bf16 v[72:75], v[162:165], v[222:225], v[72:75]
	v_mfma_f32_16x16x32_bf16 v[124:127], v[154:157], v[202:205], v[124:127]
	v_mfma_f32_16x16x32_bf16 v[120:123], v[166:169], v[202:205], v[120:123]
	v_mfma_f32_16x16x32_bf16 v[108:111], v[154:157], v[210:213], v[108:111]
	v_mfma_f32_16x16x32_bf16 v[104:107], v[166:169], v[210:213], v[104:107]
	v_mfma_f32_16x16x32_bf16 v[92:95], v[154:157], v[218:221], v[92:95]
	v_mfma_f32_16x16x32_bf16 v[88:91], v[166:169], v[218:221], v[88:91]
	v_mfma_f32_16x16x32_bf16 v[76:79], v[154:157], v[226:229], v[76:79]
	v_mfma_f32_16x16x32_bf16 v[72:75], v[166:169], v[226:229], v[72:75]
	s_setprio 0
	s_setprio 1
	v_mfma_f32_16x16x32_bf16 v[116:119], v[182:185], v[198:201], v[116:119]
	v_mfma_f32_16x16x32_bf16 v[112:115], v[190:193], v[198:201], v[112:115]
	v_mfma_f32_16x16x32_bf16 v[100:103], v[182:185], v[206:209], v[100:103]
	v_mfma_f32_16x16x32_bf16 v[96:99], v[190:193], v[206:209], v[96:99]
	v_mfma_f32_16x16x32_bf16 v[84:87], v[182:185], v[214:217], v[84:87]
	v_mfma_f32_16x16x32_bf16 v[80:83], v[190:193], v[214:217], v[80:83]
	v_mfma_f32_16x16x32_bf16 v[68:71], v[182:185], v[222:225], v[68:71]
	v_mfma_f32_16x16x32_bf16 v[64:67], v[190:193], v[222:225], v[64:67]
	v_mfma_f32_16x16x32_bf16 v[116:119], v[186:189], v[202:205], v[116:119]
	v_mfma_f32_16x16x32_bf16 v[112:115], v[194:197], v[202:205], v[112:115]
	v_mfma_f32_16x16x32_bf16 v[100:103], v[186:189], v[210:213], v[100:103]
	v_mfma_f32_16x16x32_bf16 v[96:99], v[194:197], v[210:213], v[96:99]
	v_mfma_f32_16x16x32_bf16 v[84:87], v[186:189], v[218:221], v[84:87]
	v_mfma_f32_16x16x32_bf16 v[80:83], v[194:197], v[218:221], v[80:83]
	v_mfma_f32_16x16x32_bf16 v[68:71], v[186:189], v[226:229], v[68:71]
	v_mfma_f32_16x16x32_bf16 v[64:67], v[194:197], v[226:229], v[64:67]
	s_setprio 0
	s_barrier
	s_add_i32 s36, s40, s61
	v_lshl_add_u64 v[158:159], v[158:159], 0, s[14:15]
	s_mov_b32 m0, s36
	ds_read_b128 v[198:201], v179 offset:49152
	ds_read_b128 v[202:205], v179 offset:50176
	ds_read_b128 v[206:209], v179 offset:51200
	ds_read_b128 v[210:213], v179 offset:52224
	ds_read_b128 v[214:217], v179 offset:53248
	ds_read_b128 v[218:221], v179 offset:54272
	ds_read_b128 v[222:225], v179 offset:55296
	ds_read_b128 v[226:229], v179 offset:56320
	global_load_lds_dwordx4 v[158:159], off
	s_add_i32 m0, s36, 0x2000
	s_add_u32 s8, s8, 0x40080
	v_lshl_add_u64 v[158:159], v[230:231], 0, s[14:15]
	s_addc_u32 s9, s9, 0
	s_add_i32 s36, s41, s61
	global_load_lds_dwordx4 v[158:159], off
	v_lshl_add_u64 v[158:159], s[8:9], 0, v[134:135]
	s_mov_b32 m0, s36
	s_nop 0
	global_load_lds_dwordx4 v[158:159], off
	v_lshl_add_u64 v[158:159], s[8:9], 0, v[138:139]
	s_add_i32 m0, s36, 0x2000
	s_nop 0
	global_load_lds_dwordx4 v[158:159], off
	v_lshl_add_u64 v[158:159], v[232:233], 0, s[14:15]
	s_mov_b32 m0, s76
	s_nop 0
	global_load_lds_dwordx4 v[158:159], off
	v_lshl_add_u64 v[158:159], v[234:235], 0, s[14:15]
	s_mov_b32 m0, s77
	s_nop 0
	global_load_lds_dwordx4 v[158:159], off
	s_waitcnt vmcnt(8)
	s_waitcnt lgkmcnt(0)
	s_barrier
	s_setprio 1
	s_waitcnt lgkmcnt(0)
	v_mfma_f32_16x16x32_bf16 v[60:63], v[128:131], v[198:201], v[60:63]
	v_mfma_f32_16x16x32_bf16 v[56:59], v[162:165], v[198:201], v[56:59]
	v_mfma_f32_16x16x32_bf16 v[44:47], v[128:131], v[206:209], v[44:47]
	v_mfma_f32_16x16x32_bf16 v[40:43], v[162:165], v[206:209], v[40:43]
	v_mfma_f32_16x16x32_bf16 v[28:31], v[128:131], v[214:217], v[28:31]
	v_mfma_f32_16x16x32_bf16 v[24:27], v[162:165], v[214:217], v[24:27]
	v_mfma_f32_16x16x32_bf16 v[12:15], v[128:131], v[222:225], v[12:15]
	v_mfma_f32_16x16x32_bf16 v[8:11], v[162:165], v[222:225], v[8:11]
	v_mfma_f32_16x16x32_bf16 v[60:63], v[154:157], v[202:205], v[60:63]
	v_mfma_f32_16x16x32_bf16 v[56:59], v[166:169], v[202:205], v[56:59]
	v_mfma_f32_16x16x32_bf16 v[44:47], v[154:157], v[210:213], v[44:47]
	v_mfma_f32_16x16x32_bf16 v[40:43], v[166:169], v[210:213], v[40:43]
	v_mfma_f32_16x16x32_bf16 v[28:31], v[154:157], v[218:221], v[28:31]
	v_mfma_f32_16x16x32_bf16 v[24:27], v[166:169], v[218:221], v[24:27]
	v_mfma_f32_16x16x32_bf16 v[12:15], v[154:157], v[226:229], v[12:15]
	v_mfma_f32_16x16x32_bf16 v[8:11], v[166:169], v[226:229], v[8:11]
	s_setprio 0
	s_setprio 1
	v_mfma_f32_16x16x32_bf16 v[52:55], v[182:185], v[198:201], v[52:55]
	v_mfma_f32_16x16x32_bf16 v[48:51], v[190:193], v[198:201], v[48:51]
	v_mfma_f32_16x16x32_bf16 v[36:39], v[182:185], v[206:209], v[36:39]
	v_mfma_f32_16x16x32_bf16 v[32:35], v[190:193], v[206:209], v[32:35]
	v_mfma_f32_16x16x32_bf16 v[20:23], v[182:185], v[214:217], v[20:23]
	v_mfma_f32_16x16x32_bf16 v[16:19], v[190:193], v[214:217], v[16:19]
	v_mfma_f32_16x16x32_bf16 v[4:7], v[182:185], v[222:225], v[4:7]
	v_mfma_f32_16x16x32_bf16 v[0:3], v[190:193], v[222:225], v[0:3]
	v_mfma_f32_16x16x32_bf16 v[52:55], v[186:189], v[202:205], v[52:55]
	v_mfma_f32_16x16x32_bf16 v[48:51], v[194:197], v[202:205], v[48:51]
	v_mfma_f32_16x16x32_bf16 v[36:39], v[186:189], v[210:213], v[36:39]
	v_mfma_f32_16x16x32_bf16 v[32:35], v[194:197], v[210:213], v[32:35]
	v_mfma_f32_16x16x32_bf16 v[20:23], v[186:189], v[218:221], v[20:23]
	v_mfma_f32_16x16x32_bf16 v[16:19], v[194:197], v[218:221], v[16:19]
	v_mfma_f32_16x16x32_bf16 v[4:7], v[186:189], v[226:229], v[4:7]
	v_mfma_f32_16x16x32_bf16 v[0:3], v[194:197], v[226:229], v[0:3]
	s_setprio 0
	s_barrier
	s_add_i32 s39, s39, 2
	s_add_u32 s0, s0, 0x100
	s_addc_u32 s1, s1, 0
	s_add_u32 s33, s33, 0x100
	s_addc_u32 s38, s38, 0
	s_cmp_gt_u32 s39, 13
	s_cbranch_scc0 .LBB0_799
	s_branch .Lpeel_exit_5

.LBB0_1487:
	s_ashr_i32 s15, s14, 31
	s_lshl_b64 s[16:17], s[14:15], 19
	s_add_u32 s16, s66, s16
	s_addc_u32 s17, s67, s17
	s_and_b64 s[18:19], s[4:5], exec
	s_cselect_b32 s15, s17, s1
	s_cselect_b32 s41, s16, s0
	s_ashr_i32 s13, s12, 31
	s_lshl_b64 s[18:19], s[12:13], 19
	s_add_u32 s18, s26, s18
	s_addc_u32 s19, s27, s19
	s_and_b64 s[24:25], s[4:5], exec
	s_cselect_b32 s13, s19, s23
	s_cselect_b32 s42, s18, s22
	s_add_u32 s0, s0, 0x40080
	s_addc_u32 s1, s1, 0
	s_add_u32 s43, s22, 0x100
	s_addc_u32 s44, s23, 0
	s_mov_b32 s45, -2
	v_lshl_add_u32 v248, s20, 8, v156
	v_ashrrev_i32_e32 v249, 31, v248
	v_lshl_add_u64 v[248:249], v[248:249], 2, s[8:9]
	global_load_dword v240, v[248:249], off
	global_load_dword v241, v[248:249], off offset:64
	global_load_dword v242, v[248:249], off offset:128
	global_load_dword v243, v[248:249], off offset:192
	global_load_dword v244, v[248:249], off offset:512
	global_load_dword v245, v[248:249], off offset:576
	global_load_dword v246, v[248:249], off offset:640
	global_load_dword v247, v[248:249], off offset:704
	ds_read_b128 v[144:147], v159
	ds_read_b128 v[148:151], v159 offset:1024
	ds_read_b128 v[152:155], v159 offset:2048
	ds_read_b128 v[166:169], v159 offset:3072
	ds_read_b128 v[170:173], v162
	ds_read_b128 v[174:177], v162 offset:1024
	ds_read_b128 v[178:181], v162 offset:2048
	ds_read_b128 v[188:191], v162 offset:3072
	s_add_u32 s22, s0, 0xfffc0080
	s_addc_u32 s23, s1, -1
	s_cmp_eq_u32 s45, 12
	s_cselect_b32 s25, s15, s23
	s_cselect_b32 s24, s41, s22
	s_cselect_b32 s23, s13, s44
	s_cselect_b32 s22, s42, s43
	v_lshl_add_u64 v[224:225], s[0:1], 0, v[136:137]
	s_add_i32 m0, s21, 0xc000
	ds_read_b128 v[192:195], v163
	ds_read_b128 v[196:199], v163 offset:1024
	ds_read_b128 v[200:203], v163 offset:2048
	ds_read_b128 v[204:207], v163 offset:3072
	ds_read_b128 v[208:211], v163 offset:4096
	ds_read_b128 v[212:215], v163 offset:5120
	ds_read_b128 v[216:219], v163 offset:6144
	ds_read_b128 v[220:223], v163 offset:7168
	global_load_lds_dwordx4 v[224:225], off
	v_lshl_add_u64 v[224:225], s[0:1], 0, v[138:139]
	s_add_i32 m0, s21, 0xe000
	s_nop 0
	global_load_lds_dwordx4 v[224:225], off
	s_waitcnt vmcnt(8)
	s_waitcnt lgkmcnt(0)
	s_barrier
	s_setprio 1
	s_waitcnt lgkmcnt(0)
	v_mfma_f32_16x16x32_bf16 v[124:127], v[144:147], v[192:195], 0
	v_mfma_f32_16x16x32_bf16 v[120:123], v[152:155], v[192:195], 0
	v_mfma_f32_16x16x32_bf16 v[116:119], v[144:147], v[200:203], 0
	v_mfma_f32_16x16x32_bf16 v[104:107], v[152:155], v[200:203], 0
	v_mfma_f32_16x16x32_bf16 v[92:95], v[144:147], v[208:211], 0
	v_mfma_f32_16x16x32_bf16 v[88:91], v[152:155], v[208:211], 0
	v_mfma_f32_16x16x32_bf16 v[76:79], v[144:147], v[216:219], 0
	v_mfma_f32_16x16x32_bf16 v[72:75], v[152:155], v[216:219], 0
	v_mfma_f32_16x16x32_bf16 v[124:127], v[148:151], v[196:199], v[124:127]
	v_mfma_f32_16x16x32_bf16 v[120:123], v[166:169], v[196:199], v[120:123]
	v_mfma_f32_16x16x32_bf16 v[116:119], v[148:151], v[204:207], v[116:119]
	v_mfma_f32_16x16x32_bf16 v[104:107], v[166:169], v[204:207], v[104:107]
	v_mfma_f32_16x16x32_bf16 v[92:95], v[148:151], v[212:215], v[92:95]
	v_mfma_f32_16x16x32_bf16 v[88:91], v[166:169], v[212:215], v[88:91]
	v_mfma_f32_16x16x32_bf16 v[76:79], v[148:151], v[220:223], v[76:79]
	v_mfma_f32_16x16x32_bf16 v[72:75], v[166:169], v[220:223], v[72:75]
	s_setprio 0
	s_setprio 1
	v_mfma_f32_16x16x32_bf16 v[112:115], v[170:173], v[192:195], 0
	v_mfma_f32_16x16x32_bf16 v[108:111], v[178:181], v[192:195], 0
	v_mfma_f32_16x16x32_bf16 v[100:103], v[170:173], v[200:203], 0
	v_mfma_f32_16x16x32_bf16 v[96:99], v[178:181], v[200:203], 0
	v_mfma_f32_16x16x32_bf16 v[84:87], v[170:173], v[208:211], 0
	v_mfma_f32_16x16x32_bf16 v[80:83], v[178:181], v[208:211], 0
	v_mfma_f32_16x16x32_bf16 v[68:71], v[170:173], v[216:219], 0
	v_mfma_f32_16x16x32_bf16 v[64:67], v[178:181], v[216:219], 0
	v_mfma_f32_16x16x32_bf16 v[112:115], v[174:177], v[196:199], v[112:115]
	v_mfma_f32_16x16x32_bf16 v[108:111], v[188:191], v[196:199], v[108:111]
	v_mfma_f32_16x16x32_bf16 v[100:103], v[174:177], v[204:207], v[100:103]
	v_mfma_f32_16x16x32_bf16 v[96:99], v[188:191], v[204:207], v[96:99]
	v_mfma_f32_16x16x32_bf16 v[84:87], v[174:177], v[212:215], v[84:87]
	v_mfma_f32_16x16x32_bf16 v[80:83], v[188:191], v[212:215], v[80:83]
	v_mfma_f32_16x16x32_bf16 v[68:71], v[174:177], v[220:223], v[68:71]
	v_mfma_f32_16x16x32_bf16 v[64:67], v[188:191], v[220:223], v[64:67]
	s_setprio 0
	s_barrier
	s_add_i32 s46, s39, s28
	v_lshl_add_u64 v[224:225], s[22:23], 0, v[132:133]
	s_mov_b32 m0, s46
	ds_read_b128 v[192:195], v163 offset:16384
	ds_read_b128 v[196:199], v163 offset:17408
	ds_read_b128 v[200:203], v163 offset:18432
	ds_read_b128 v[204:207], v163 offset:19456
	ds_read_b128 v[208:211], v163 offset:20480
	ds_read_b128 v[212:215], v163 offset:21504
	ds_read_b128 v[216:219], v163 offset:22528
	ds_read_b128 v[220:223], v163 offset:23552
	global_load_lds_dwordx4 v[224:225], off
	s_add_i32 m0, s46, 0x2000
	s_add_u32 s46, s22, 0x40000
	v_lshl_add_u64 v[226:227], s[22:23], 0, v[128:129]
	s_addc_u32 s47, s23, 0
	s_add_i32 s48, s40, s28
	global_load_lds_dwordx4 v[226:227], off
	v_lshl_add_u64 v[228:229], s[46:47], 0, v[132:133]
	s_mov_b32 m0, s48
	v_lshl_add_u64 v[230:231], s[24:25], 0, v[130:131]
	global_load_lds_dwordx4 v[228:229], off
	v_lshl_add_u64 v[228:229], s[46:47], 0, v[128:129]
	s_add_i32 m0, s48, 0x2000
	s_nop 0
	global_load_lds_dwordx4 v[228:229], off
	v_lshl_add_u64 v[228:229], s[24:25], 0, v[134:135]
	s_mov_b32 m0, s21
	s_nop 0
	global_load_lds_dwordx4 v[228:229], off
	s_mov_b32 m0, s31
	s_nop 0
	global_load_lds_dwordx4 v[230:231], off
	s_waitcnt vmcnt(8)
	s_waitcnt lgkmcnt(0)
	s_barrier
	s_setprio 1
	s_waitcnt lgkmcnt(0)
	v_mfma_f32_16x16x32_bf16 v[60:63], v[144:147], v[192:195], 0
	v_mfma_f32_16x16x32_bf16 v[56:59], v[152:155], v[192:195], 0
	v_mfma_f32_16x16x32_bf16 v[44:47], v[144:147], v[200:203], 0
	v_mfma_f32_16x16x32_bf16 v[40:43], v[152:155], v[200:203], 0
	v_mfma_f32_16x16x32_bf16 v[28:31], v[144:147], v[208:211], 0
	v_mfma_f32_16x16x32_bf16 v[24:27], v[152:155], v[208:211], 0
	v_mfma_f32_16x16x32_bf16 v[12:15], v[144:147], v[216:219], 0
	v_mfma_f32_16x16x32_bf16 v[8:11], v[152:155], v[216:219], 0
	v_mfma_f32_16x16x32_bf16 v[60:63], v[148:151], v[196:199], v[60:63]
	v_mfma_f32_16x16x32_bf16 v[56:59], v[166:169], v[196:199], v[56:59]
	v_mfma_f32_16x16x32_bf16 v[44:47], v[148:151], v[204:207], v[44:47]
	v_mfma_f32_16x16x32_bf16 v[40:43], v[166:169], v[204:207], v[40:43]
	v_mfma_f32_16x16x32_bf16 v[28:31], v[148:151], v[212:215], v[28:31]
	v_mfma_f32_16x16x32_bf16 v[24:27], v[166:169], v[212:215], v[24:27]
	v_mfma_f32_16x16x32_bf16 v[12:15], v[148:151], v[220:223], v[12:15]
	v_mfma_f32_16x16x32_bf16 v[8:11], v[166:169], v[220:223], v[8:11]
	s_setprio 0
	s_setprio 1
	v_mfma_f32_16x16x32_bf16 v[52:55], v[170:173], v[192:195], 0
	v_mfma_f32_16x16x32_bf16 v[48:51], v[178:181], v[192:195], 0
	v_mfma_f32_16x16x32_bf16 v[36:39], v[170:173], v[200:203], 0
	v_mfma_f32_16x16x32_bf16 v[32:35], v[178:181], v[200:203], 0
	v_mfma_f32_16x16x32_bf16 v[20:23], v[170:173], v[208:211], 0
	v_mfma_f32_16x16x32_bf16 v[16:19], v[178:181], v[208:211], 0
	v_mfma_f32_16x16x32_bf16 v[4:7], v[170:173], v[216:219], 0
	v_mfma_f32_16x16x32_bf16 v[0:3], v[178:181], v[216:219], 0
	v_mfma_f32_16x16x32_bf16 v[52:55], v[174:177], v[196:199], v[52:55]
	v_mfma_f32_16x16x32_bf16 v[48:51], v[188:191], v[196:199], v[48:51]
	v_mfma_f32_16x16x32_bf16 v[36:39], v[174:177], v[204:207], v[36:39]
	v_mfma_f32_16x16x32_bf16 v[32:35], v[188:191], v[204:207], v[32:35]
	v_mfma_f32_16x16x32_bf16 v[20:23], v[174:177], v[212:215], v[20:23]
	v_mfma_f32_16x16x32_bf16 v[16:19], v[188:191], v[212:215], v[16:19]
	v_mfma_f32_16x16x32_bf16 v[4:7], v[174:177], v[220:223], v[4:7]
	v_mfma_f32_16x16x32_bf16 v[0:3], v[188:191], v[220:223], v[0:3]
	s_setprio 0
	s_barrier
	s_add_i32 s46, 0, 0x18000
	v_add_u32_e32 v165, s46, v157
	s_add_i32 s47, 0, 0x1c000
	ds_read_b128 v[144:147], v165
	ds_read_b128 v[148:151], v165 offset:1024
	ds_read_b128 v[152:155], v165 offset:2048
	ds_read_b128 v[166:169], v165 offset:3072
	v_add_u32_e32 v165, s47, v157
	ds_read_b128 v[170:173], v165
	ds_read_b128 v[174:177], v165 offset:1024
	ds_read_b128 v[178:181], v165 offset:2048
	ds_read_b128 v[188:191], v165 offset:3072
	s_add_u32 s24, s24, 0x40000
	s_addc_u32 s25, s25, 0
	s_mov_b32 m0, s34
	v_lshl_add_u64 v[232:233], s[24:25], 0, v[134:135]
	ds_read_b128 v[192:195], v163 offset:32768
	ds_read_b128 v[196:199], v163 offset:33792
	ds_read_b128 v[200:203], v163 offset:34816
	ds_read_b128 v[204:207], v163 offset:35840
	ds_read_b128 v[208:211], v163 offset:36864
	ds_read_b128 v[212:215], v163 offset:37888
	ds_read_b128 v[216:219], v163 offset:38912
	ds_read_b128 v[220:223], v163 offset:39936
	global_load_lds_dwordx4 v[232:233], off
	v_lshl_add_u64 v[232:233], s[24:25], 0, v[130:131]
	s_mov_b32 m0, s35
	s_nop 0
	global_load_lds_dwordx4 v[232:233], off
	s_waitcnt vmcnt(8)
	s_waitcnt lgkmcnt(0)
	s_barrier
	s_setprio 1
	s_waitcnt lgkmcnt(0)
	v_mfma_f32_16x16x32_bf16 v[124:127], v[144:147], v[192:195], v[124:127]
	v_mfma_f32_16x16x32_bf16 v[120:123], v[152:155], v[192:195], v[120:123]
	v_mfma_f32_16x16x32_bf16 v[116:119], v[144:147], v[200:203], v[116:119]
	v_mfma_f32_16x16x32_bf16 v[104:107], v[152:155], v[200:203], v[104:107]
	v_mfma_f32_16x16x32_bf16 v[92:95], v[144:147], v[208:211], v[92:95]
	v_mfma_f32_16x16x32_bf16 v[88:91], v[152:155], v[208:211], v[88:91]
	v_mfma_f32_16x16x32_bf16 v[76:79], v[144:147], v[216:219], v[76:79]
	v_mfma_f32_16x16x32_bf16 v[72:75], v[152:155], v[216:219], v[72:75]
	v_mfma_f32_16x16x32_bf16 v[124:127], v[148:151], v[196:199], v[124:127]
	v_mfma_f32_16x16x32_bf16 v[120:123], v[166:169], v[196:199], v[120:123]
	v_mfma_f32_16x16x32_bf16 v[116:119], v[148:151], v[204:207], v[116:119]
	v_mfma_f32_16x16x32_bf16 v[104:107], v[166:169], v[204:207], v[104:107]
	v_mfma_f32_16x16x32_bf16 v[92:95], v[148:151], v[212:215], v[92:95]
	v_mfma_f32_16x16x32_bf16 v[88:91], v[166:169], v[212:215], v[88:91]
	v_mfma_f32_16x16x32_bf16 v[76:79], v[148:151], v[220:223], v[76:79]
	v_mfma_f32_16x16x32_bf16 v[72:75], v[166:169], v[220:223], v[72:75]
	s_setprio 0
	s_setprio 1
	v_mfma_f32_16x16x32_bf16 v[112:115], v[170:173], v[192:195], v[112:115]
	v_mfma_f32_16x16x32_bf16 v[108:111], v[178:181], v[192:195], v[108:111]
	v_mfma_f32_16x16x32_bf16 v[100:103], v[170:173], v[200:203], v[100:103]
	v_mfma_f32_16x16x32_bf16 v[96:99], v[178:181], v[200:203], v[96:99]
	v_mfma_f32_16x16x32_bf16 v[84:87], v[170:173], v[208:211], v[84:87]
	v_mfma_f32_16x16x32_bf16 v[80:83], v[178:181], v[208:211], v[80:83]
	v_mfma_f32_16x16x32_bf16 v[68:71], v[170:173], v[216:219], v[68:71]
	v_mfma_f32_16x16x32_bf16 v[64:67], v[178:181], v[216:219], v[64:67]
	v_mfma_f32_16x16x32_bf16 v[112:115], v[174:177], v[196:199], v[112:115]
	v_mfma_f32_16x16x32_bf16 v[108:111], v[188:191], v[196:199], v[108:111]
	v_mfma_f32_16x16x32_bf16 v[100:103], v[174:177], v[204:207], v[100:103]
	v_mfma_f32_16x16x32_bf16 v[96:99], v[188:191], v[204:207], v[96:99]
	v_mfma_f32_16x16x32_bf16 v[84:87], v[174:177], v[212:215], v[84:87]
	v_mfma_f32_16x16x32_bf16 v[80:83], v[188:191], v[212:215], v[80:83]
	v_mfma_f32_16x16x32_bf16 v[68:71], v[174:177], v[220:223], v[68:71]
	v_mfma_f32_16x16x32_bf16 v[64:67], v[188:191], v[220:223], v[64:67]
	s_setprio 0
	s_barrier
	s_add_i32 s24, s46, s28
	v_lshl_add_u64 v[224:225], v[224:225], 0, s[6:7]
	s_mov_b32 m0, s24
	ds_read_b128 v[192:195], v163 offset:49152
	ds_read_b128 v[196:199], v163 offset:50176
	ds_read_b128 v[200:203], v163 offset:51200
	ds_read_b128 v[204:207], v163 offset:52224
	ds_read_b128 v[208:211], v163 offset:53248
	ds_read_b128 v[212:215], v163 offset:54272
	ds_read_b128 v[216:219], v163 offset:55296
	ds_read_b128 v[220:223], v163 offset:56320
	global_load_lds_dwordx4 v[224:225], off
	s_add_i32 m0, s24, 0x2000
	s_add_u32 s22, s22, 0x40080
	v_lshl_add_u64 v[224:225], v[226:227], 0, s[6:7]
	s_addc_u32 s23, s23, 0
	s_add_i32 s24, s47, s28
	global_load_lds_dwordx4 v[224:225], off
	v_lshl_add_u64 v[224:225], s[22:23], 0, v[132:133]
	s_mov_b32 m0, s24
	s_nop 0
	global_load_lds_dwordx4 v[224:225], off
	v_lshl_add_u64 v[224:225], s[22:23], 0, v[128:129]
	s_add_i32 m0, s24, 0x2000
	s_nop 0
	global_load_lds_dwordx4 v[224:225], off
	v_lshl_add_u64 v[224:225], v[228:229], 0, s[6:7]
	s_mov_b32 m0, s37
	s_nop 0
	global_load_lds_dwordx4 v[224:225], off
	v_lshl_add_u64 v[224:225], v[230:231], 0, s[6:7]
	s_mov_b32 m0, s38
	s_nop 0
	global_load_lds_dwordx4 v[224:225], off
	s_waitcnt vmcnt(8)
	s_waitcnt lgkmcnt(0)
	s_barrier
	s_setprio 1
	s_waitcnt lgkmcnt(0)
	v_mfma_f32_16x16x32_bf16 v[60:63], v[144:147], v[192:195], v[60:63]
	v_mfma_f32_16x16x32_bf16 v[56:59], v[152:155], v[192:195], v[56:59]
	v_mfma_f32_16x16x32_bf16 v[44:47], v[144:147], v[200:203], v[44:47]
	v_mfma_f32_16x16x32_bf16 v[40:43], v[152:155], v[200:203], v[40:43]
	v_mfma_f32_16x16x32_bf16 v[28:31], v[144:147], v[208:211], v[28:31]
	v_mfma_f32_16x16x32_bf16 v[24:27], v[152:155], v[208:211], v[24:27]
	v_mfma_f32_16x16x32_bf16 v[12:15], v[144:147], v[216:219], v[12:15]
	v_mfma_f32_16x16x32_bf16 v[8:11], v[152:155], v[216:219], v[8:11]
	v_mfma_f32_16x16x32_bf16 v[60:63], v[148:151], v[196:199], v[60:63]
	v_mfma_f32_16x16x32_bf16 v[56:59], v[166:169], v[196:199], v[56:59]
	v_mfma_f32_16x16x32_bf16 v[44:47], v[148:151], v[204:207], v[44:47]
	v_mfma_f32_16x16x32_bf16 v[40:43], v[166:169], v[204:207], v[40:43]
	v_mfma_f32_16x16x32_bf16 v[28:31], v[148:151], v[212:215], v[28:31]
	v_mfma_f32_16x16x32_bf16 v[24:27], v[166:169], v[212:215], v[24:27]
	v_mfma_f32_16x16x32_bf16 v[12:15], v[148:151], v[220:223], v[12:15]
	v_mfma_f32_16x16x32_bf16 v[8:11], v[166:169], v[220:223], v[8:11]
	s_setprio 0
	s_setprio 1
	v_mfma_f32_16x16x32_bf16 v[52:55], v[170:173], v[192:195], v[52:55]
	v_mfma_f32_16x16x32_bf16 v[48:51], v[178:181], v[192:195], v[48:51]
	v_mfma_f32_16x16x32_bf16 v[36:39], v[170:173], v[200:203], v[36:39]
	v_mfma_f32_16x16x32_bf16 v[32:35], v[178:181], v[200:203], v[32:35]
	v_mfma_f32_16x16x32_bf16 v[20:23], v[170:173], v[208:211], v[20:23]
	v_mfma_f32_16x16x32_bf16 v[16:19], v[178:181], v[208:211], v[16:19]
	v_mfma_f32_16x16x32_bf16 v[4:7], v[170:173], v[216:219], v[4:7]
	v_mfma_f32_16x16x32_bf16 v[0:3], v[178:181], v[216:219], v[0:3]
	v_mfma_f32_16x16x32_bf16 v[52:55], v[174:177], v[196:199], v[52:55]
	v_mfma_f32_16x16x32_bf16 v[48:51], v[188:191], v[196:199], v[48:51]
	v_mfma_f32_16x16x32_bf16 v[36:39], v[174:177], v[204:207], v[36:39]
	v_mfma_f32_16x16x32_bf16 v[32:35], v[188:191], v[204:207], v[32:35]
	v_mfma_f32_16x16x32_bf16 v[20:23], v[174:177], v[212:215], v[20:23]
	v_mfma_f32_16x16x32_bf16 v[16:19], v[188:191], v[212:215], v[16:19]
	v_mfma_f32_16x16x32_bf16 v[4:7], v[174:177], v[220:223], v[4:7]
	v_mfma_f32_16x16x32_bf16 v[0:3], v[188:191], v[220:223], v[0:3]
	s_setprio 0
	s_barrier
	s_add_i32 s45, s45, 2
	s_add_u32 s0, s0, 0x100
	s_addc_u32 s1, s1, 0
	s_add_u32 s43, s43, 0x100
	s_addc_u32 s44, s44, 0
	s_cmp_gt_u32 s45, 13
	s_cbranch_scc0 .LBB0_1488
	s_branch .Lpeel_exit_7

.LBB0_1491:
	v_lshl_add_u32 v146, s20, 8, v156
	v_ashrrev_i32_e32 v147, 31, v146
	v_lshl_add_u64 v[144:145], v[146:147], 2, s[8:9]
	v_or_b32_e32 v166, 16, v146
	v_ashrrev_i32_e32 v167, 31, v166
	v_lshl_add_u64 v[144:145], v[166:167], 2, s[8:9]
	v_lshl_or_b32 v168, s33, 8, v158
	v_or_b32_e32 v170, 32, v146
	v_or_b32_e32 v154, 48, v146
	v_add_u32_e32 v148, 0xa0, v146
	v_add_u32_e32 v152, 0x80, v146
	v_add_u32_e32 v150, 0x90, v146
	v_add_u32_e32 v144, 0xb0, v146
	v_ashrrev_i32_e32 v169, 31, v168
	v_ashrrev_i32_e32 v171, 31, v170
	v_ashrrev_i32_e32 v155, 31, v154
	v_ashrrev_i32_e32 v149, 31, v148
	v_ashrrev_i32_e32 v153, 31, v152
	v_ashrrev_i32_e32 v151, 31, v150
	v_ashrrev_i32_e32 v145, 31, v144
	v_lshlrev_b64 v[172:173], 13, v[146:147]
	v_lshlrev_b64 v[146:147], 1, v[168:169]
	v_lshl_add_u64 v[168:169], v[170:171], 2, s[8:9]
	v_lshl_add_u64 v[174:175], v[154:155], 2, s[8:9]
	v_lshl_add_u64 v[180:181], v[148:149], 2, s[8:9]
	v_lshl_add_u64 v[176:177], v[152:153], 2, s[8:9]
	v_lshl_add_u64 v[178:179], v[150:151], 2, s[8:9]
	v_lshl_add_u64 v[188:189], v[144:145], 2, s[8:9]
	s_nop 0
	s_nop 0
	s_nop 0
	s_nop 0
	v_lshl_add_u64 v[172:173], s[68:69], 0, v[172:173]
	v_lshl_add_u64 v[172:173], v[172:173], 0, v[146:147]
	v_lshlrev_b64 v[166:167], 13, v[166:167]
	s_andn2_b64 vcc, exec, s[4:5]
	s_mov_b64 s[0:1], -1
	v_fmamk_f32 v168, v240, 0x3a800000, v164
	v_rsq_f32_e32 v168, v168
	v_fmamk_f32 v169, v241, 0x3a800000, v164
	v_rsq_f32_e32 v174, v169
	v_pk_mul_f32 v[126:127], v[126:127], v[168:169] op_sel_hi:[1,0]
	v_pk_mul_f32 v[124:125], v[124:125], v[168:169] op_sel_hi:[1,0]
	v_pk_mul_f32 v[122:123], v[122:123], v[168:169] op_sel_hi:[1,0]
	v_pk_mul_f32 v[120:121], v[120:121], v[168:169] op_sel_hi:[1,0]
	v_pk_mul_f32 v[114:115], v[114:115], v[168:169] op_sel_hi:[1,0]
	v_pk_mul_f32 v[112:113], v[112:113], v[168:169] op_sel_hi:[1,0]
	v_pk_mul_f32 v[110:111], v[110:111], v[168:169] op_sel_hi:[1,0]
	v_pk_mul_f32 v[108:109], v[108:109], v[168:169] op_sel_hi:[1,0]
	v_max_f32_e32 v124, 0, v124
	v_max_f32_e32 v120, 0, v120
	v_max_f32_e32 v125, 0, v125
	v_max_f32_e32 v121, 0, v121
	v_max_f32_e32 v126, 0, v126
	v_max_f32_e32 v122, 0, v122
	v_max_f32_e32 v127, 0, v127
	v_max_f32_e32 v123, 0, v123
	v_max_f32_e32 v112, 0, v112
	v_max_f32_e32 v113, 0, v113
	v_max_f32_e32 v114, 0, v114
	v_max_f32_e32 v115, 0, v115
	v_max_f32_e32 v108, 0, v108
	v_max_f32_e32 v109, 0, v109
	v_max_f32_e32 v110, 0, v110
	v_max_f32_e32 v111, 0, v111
	v_pk_mul_f32 v[168:169], v[106:107], v[174:175] op_sel_hi:[1,0]
	v_pk_mul_f32 v[104:105], v[104:105], v[174:175] op_sel_hi:[1,0]
	v_pk_mul_f32 v[106:107], v[124:125], v[124:125]
	v_pk_mul_f32 v[120:121], v[120:121], v[120:121]
	v_pk_mul_f32 v[124:125], v[126:127], v[126:127]
	v_pk_mul_f32 v[122:123], v[122:123], v[122:123]
	v_pk_mul_f32 v[112:113], v[112:113], v[112:113]
	v_pk_mul_f32 v[114:115], v[114:115], v[114:115]
	v_pk_mul_f32 v[118:119], v[118:119], v[174:175] op_sel_hi:[1,0]
	v_pk_mul_f32 v[116:117], v[116:117], v[174:175] op_sel_hi:[1,0]
	v_pk_mul_f32 v[126:127], v[108:109], v[108:109]
	v_pk_mul_f32 v[176:177], v[110:111], v[110:111]
	v_max_f32_e32 v178, 0, v104
	v_max_f32_e32 v179, 0, v105
	v_cvt_pk_bf16_f32 v104, v106, v107
	v_cvt_pk_bf16_f32 v105, v124, v125
	v_cvt_pk_bf16_f32 v106, v120, v121
	v_cvt_pk_bf16_f32 v107, v122, v123
	v_cvt_pk_bf16_f32 v108, v112, v113
	v_cvt_pk_bf16_f32 v109, v114, v115
	v_max_f32_e32 v116, 0, v116
	v_max_f32_e32 v117, 0, v117
	v_cvt_pk_bf16_f32 v110, v126, v127
	v_cvt_pk_bf16_f32 v111, v176, v177
	global_store_dwordx4 v[172:173], v[104:107], off
	global_store_dwordx4 v[172:173], v[108:111], off offset:256
	v_pk_mul_f32 v[100:101], v[100:101], v[174:175] op_sel_hi:[1,0]
	v_pk_mul_f32 v[104:105], v[116:117], v[116:117]
	v_max_f32_e32 v108, 0, v118
	v_max_f32_e32 v109, 0, v119
	v_max_f32_e32 v110, 0, v168
	v_max_f32_e32 v111, 0, v169
	v_pk_mul_f32 v[108:109], v[108:109], v[108:109]
	v_pk_mul_f32 v[106:107], v[178:179], v[178:179]
	v_pk_mul_f32 v[110:111], v[110:111], v[110:111]
	v_cvt_pk_bf16_f32 v104, v104, v105
	v_cvt_pk_bf16_f32 v105, v108, v109
	v_lshl_add_u64 v[108:109], s[68:69], 0, v[166:167]
	v_pk_mul_f32 v[98:99], v[98:99], v[174:175] op_sel_hi:[1,0]
	v_pk_mul_f32 v[96:97], v[96:97], v[174:175] op_sel_hi:[1,0]
	v_cvt_pk_bf16_f32 v106, v106, v107
	v_cvt_pk_bf16_f32 v107, v110, v111
	v_lshl_add_u64 v[108:109], v[108:109], 0, v[146:147]
	v_pk_mul_f32 v[102:103], v[102:103], v[174:175] op_sel_hi:[1,0]
	v_max_f32_e32 v100, 0, v100
	v_max_f32_e32 v96, 0, v96
	v_max_f32_e32 v101, 0, v101
	v_max_f32_e32 v97, 0, v97
	v_max_f32_e32 v98, 0, v98
	v_max_f32_e32 v99, 0, v99
	global_store_dwordx4 v[108:109], v[104:107], off
	v_pk_mul_f32 v[100:101], v[100:101], v[100:101]
	s_nop 0
	v_pk_mul_f32 v[104:105], v[96:97], v[96:97]
	v_max_f32_e32 v96, 0, v102
	v_max_f32_e32 v97, 0, v103
	v_pk_mul_f32 v[106:107], v[98:99], v[98:99]
	v_fmamk_f32 v99, v242, 0x3a800000, v164
	v_pk_mul_f32 v[102:103], v[96:97], v[96:97]
	v_cvt_pk_bf16_f32 v96, v100, v101
	v_rsq_f32_e32 v100, v99
	v_cvt_pk_bf16_f32 v97, v102, v103
	v_cvt_pk_bf16_f32 v98, v104, v105
	v_cvt_pk_bf16_f32 v99, v106, v107
	v_pk_mul_f32 v[92:93], v[92:93], v[100:101] op_sel_hi:[1,0]
	v_pk_mul_f32 v[88:89], v[88:89], v[100:101] op_sel_hi:[1,0]
	v_pk_mul_f32 v[94:95], v[94:95], v[100:101] op_sel_hi:[1,0]
	v_pk_mul_f32 v[90:91], v[90:91], v[100:101] op_sel_hi:[1,0]
	v_max_f32_e32 v92, 0, v92
	v_max_f32_e32 v88, 0, v88
	v_max_f32_e32 v93, 0, v93
	v_max_f32_e32 v89, 0, v89
	global_store_dwordx4 v[108:109], v[96:99], off offset:256
	v_pk_mul_f32 v[92:93], v[92:93], v[92:93]
	v_max_f32_e32 v90, 0, v90
	v_lshlrev_b64 v[96:97], 13, v[170:171]
	v_pk_mul_f32 v[98:99], v[88:89], v[88:89]
	v_max_f32_e32 v88, 0, v94
	v_max_f32_e32 v89, 0, v95
	v_max_f32_e32 v91, 0, v91
	v_pk_mul_f32 v[94:95], v[88:89], v[88:89]
	v_pk_mul_f32 v[102:103], v[90:91], v[90:91]
	v_cvt_pk_bf16_f32 v88, v92, v93
	v_lshl_add_u64 v[92:93], s[68:69], 0, v[96:97]
	v_pk_mul_f32 v[84:85], v[84:85], v[100:101] op_sel_hi:[1,0]
	v_pk_mul_f32 v[82:83], v[82:83], v[100:101] op_sel_hi:[1,0]
	v_pk_mul_f32 v[80:81], v[80:81], v[100:101] op_sel_hi:[1,0]
	v_cvt_pk_bf16_f32 v89, v94, v95
	v_cvt_pk_bf16_f32 v90, v98, v99
	v_cvt_pk_bf16_f32 v91, v102, v103
	v_lshl_add_u64 v[92:93], v[92:93], 0, v[146:147]
	v_pk_mul_f32 v[86:87], v[86:87], v[100:101] op_sel_hi:[1,0]
	v_max_f32_e32 v84, 0, v84
	v_max_f32_e32 v80, 0, v80
	v_max_f32_e32 v85, 0, v85
	v_max_f32_e32 v81, 0, v81
	v_max_f32_e32 v82, 0, v82
	v_max_f32_e32 v83, 0, v83
	global_store_dwordx4 v[92:93], v[88:91], off
	v_pk_mul_f32 v[84:85], v[84:85], v[84:85]
	s_nop 0
	v_pk_mul_f32 v[88:89], v[80:81], v[80:81]
	v_max_f32_e32 v80, 0, v86
	v_max_f32_e32 v81, 0, v87
	v_pk_mul_f32 v[90:91], v[82:83], v[82:83]
	v_fmamk_f32 v83, v243, 0x3a800000, v164
	v_pk_mul_f32 v[86:87], v[80:81], v[80:81]
	v_cvt_pk_bf16_f32 v80, v84, v85
	v_rsq_f32_e32 v84, v83
	v_cvt_pk_bf16_f32 v81, v86, v87
	v_cvt_pk_bf16_f32 v82, v88, v89
	v_cvt_pk_bf16_f32 v83, v90, v91
	v_pk_mul_f32 v[76:77], v[76:77], v[84:85] op_sel_hi:[1,0]
	v_pk_mul_f32 v[72:73], v[72:73], v[84:85] op_sel_hi:[1,0]
	v_pk_mul_f32 v[78:79], v[78:79], v[84:85] op_sel_hi:[1,0]
	v_pk_mul_f32 v[74:75], v[74:75], v[84:85] op_sel_hi:[1,0]
	v_max_f32_e32 v76, 0, v76
	v_max_f32_e32 v72, 0, v72
	v_max_f32_e32 v77, 0, v77
	v_max_f32_e32 v73, 0, v73
	global_store_dwordx4 v[92:93], v[80:83], off offset:256
	v_pk_mul_f32 v[76:77], v[76:77], v[76:77]
	v_max_f32_e32 v74, 0, v74
	v_lshlrev_b64 v[80:81], 13, v[154:155]
	v_pk_mul_f32 v[82:83], v[72:73], v[72:73]
	v_max_f32_e32 v72, 0, v78
	v_max_f32_e32 v73, 0, v79
	v_max_f32_e32 v75, 0, v75
	v_pk_mul_f32 v[78:79], v[72:73], v[72:73]
	v_pk_mul_f32 v[86:87], v[74:75], v[74:75]
	v_cvt_pk_bf16_f32 v72, v76, v77
	v_lshl_add_u64 v[76:77], s[68:69], 0, v[80:81]
	v_pk_mul_f32 v[68:69], v[68:69], v[84:85] op_sel_hi:[1,0]
	v_pk_mul_f32 v[66:67], v[66:67], v[84:85] op_sel_hi:[1,0]
	v_pk_mul_f32 v[64:65], v[64:65], v[84:85] op_sel_hi:[1,0]
	v_cvt_pk_bf16_f32 v73, v78, v79
	v_cvt_pk_bf16_f32 v74, v82, v83
	v_cvt_pk_bf16_f32 v75, v86, v87
	v_lshl_add_u64 v[76:77], v[76:77], 0, v[146:147]
	v_pk_mul_f32 v[70:71], v[70:71], v[84:85] op_sel_hi:[1,0]
	v_max_f32_e32 v68, 0, v68
	v_max_f32_e32 v64, 0, v64
	v_max_f32_e32 v69, 0, v69
	v_max_f32_e32 v65, 0, v65
	v_max_f32_e32 v66, 0, v66
	v_max_f32_e32 v67, 0, v67
	global_store_dwordx4 v[76:77], v[72:75], off
	v_pk_mul_f32 v[68:69], v[68:69], v[68:69]
	s_nop 0
	v_pk_mul_f32 v[72:73], v[64:65], v[64:65]
	v_max_f32_e32 v64, 0, v70
	v_max_f32_e32 v65, 0, v71
	v_pk_mul_f32 v[74:75], v[66:67], v[66:67]
	v_fmamk_f32 v67, v244, 0x3a800000, v164
	v_pk_mul_f32 v[70:71], v[64:65], v[64:65]
	v_cvt_pk_bf16_f32 v64, v68, v69
	v_rsq_f32_e32 v68, v67
	v_cvt_pk_bf16_f32 v65, v70, v71
	v_cvt_pk_bf16_f32 v66, v72, v73
	v_cvt_pk_bf16_f32 v67, v74, v75
	v_pk_mul_f32 v[60:61], v[60:61], v[68:69] op_sel_hi:[1,0]
	v_pk_mul_f32 v[56:57], v[56:57], v[68:69] op_sel_hi:[1,0]
	v_pk_mul_f32 v[62:63], v[62:63], v[68:69] op_sel_hi:[1,0]
	v_pk_mul_f32 v[58:59], v[58:59], v[68:69] op_sel_hi:[1,0]
	v_max_f32_e32 v60, 0, v60
	v_max_f32_e32 v56, 0, v56
	v_max_f32_e32 v61, 0, v61
	v_max_f32_e32 v57, 0, v57
	global_store_dwordx4 v[76:77], v[64:67], off offset:256
	v_pk_mul_f32 v[60:61], v[60:61], v[60:61]
	v_max_f32_e32 v58, 0, v58
	v_lshlrev_b64 v[64:65], 13, v[152:153]
	v_pk_mul_f32 v[66:67], v[56:57], v[56:57]
	v_max_f32_e32 v56, 0, v62
	v_max_f32_e32 v57, 0, v63
	v_max_f32_e32 v59, 0, v59
	v_pk_mul_f32 v[62:63], v[56:57], v[56:57]
	v_pk_mul_f32 v[70:71], v[58:59], v[58:59]
	v_cvt_pk_bf16_f32 v56, v60, v61
	v_lshl_add_u64 v[60:61], s[68:69], 0, v[64:65]
	v_pk_mul_f32 v[52:53], v[52:53], v[68:69] op_sel_hi:[1,0]
	v_pk_mul_f32 v[50:51], v[50:51], v[68:69] op_sel_hi:[1,0]
	v_pk_mul_f32 v[48:49], v[48:49], v[68:69] op_sel_hi:[1,0]
	v_cvt_pk_bf16_f32 v57, v62, v63
	v_cvt_pk_bf16_f32 v58, v66, v67
	v_cvt_pk_bf16_f32 v59, v70, v71
	v_lshl_add_u64 v[60:61], v[60:61], 0, v[146:147]
	v_pk_mul_f32 v[54:55], v[54:55], v[68:69] op_sel_hi:[1,0]
	v_max_f32_e32 v52, 0, v52
	v_max_f32_e32 v48, 0, v48
	v_max_f32_e32 v53, 0, v53
	v_max_f32_e32 v49, 0, v49
	v_max_f32_e32 v50, 0, v50
	v_max_f32_e32 v51, 0, v51
	global_store_dwordx4 v[60:61], v[56:59], off
	v_pk_mul_f32 v[52:53], v[52:53], v[52:53]
	s_nop 0
	v_pk_mul_f32 v[56:57], v[48:49], v[48:49]
	v_max_f32_e32 v48, 0, v54
	v_max_f32_e32 v49, 0, v55
	v_pk_mul_f32 v[58:59], v[50:51], v[50:51]
	v_fmamk_f32 v51, v245, 0x3a800000, v164
	v_pk_mul_f32 v[54:55], v[48:49], v[48:49]
	v_cvt_pk_bf16_f32 v48, v52, v53
	v_rsq_f32_e32 v52, v51
	v_cvt_pk_bf16_f32 v49, v54, v55
	v_cvt_pk_bf16_f32 v50, v56, v57
	v_cvt_pk_bf16_f32 v51, v58, v59
	v_pk_mul_f32 v[44:45], v[44:45], v[52:53] op_sel_hi:[1,0]
	v_pk_mul_f32 v[40:41], v[40:41], v[52:53] op_sel_hi:[1,0]
	v_pk_mul_f32 v[46:47], v[46:47], v[52:53] op_sel_hi:[1,0]
	v_pk_mul_f32 v[42:43], v[42:43], v[52:53] op_sel_hi:[1,0]
	v_max_f32_e32 v44, 0, v44
	v_max_f32_e32 v40, 0, v40
	v_max_f32_e32 v45, 0, v45
	v_max_f32_e32 v41, 0, v41
	global_store_dwordx4 v[60:61], v[48:51], off offset:256
	v_pk_mul_f32 v[44:45], v[44:45], v[44:45]
	v_max_f32_e32 v42, 0, v42
	v_lshlrev_b64 v[48:49], 13, v[150:151]
	v_pk_mul_f32 v[50:51], v[40:41], v[40:41]
	v_max_f32_e32 v40, 0, v46
	v_max_f32_e32 v41, 0, v47
	v_max_f32_e32 v43, 0, v43
	v_pk_mul_f32 v[46:47], v[40:41], v[40:41]
	v_pk_mul_f32 v[54:55], v[42:43], v[42:43]
	v_cvt_pk_bf16_f32 v40, v44, v45
	v_lshl_add_u64 v[44:45], s[68:69], 0, v[48:49]
	v_pk_mul_f32 v[36:37], v[36:37], v[52:53] op_sel_hi:[1,0]
	v_pk_mul_f32 v[34:35], v[34:35], v[52:53] op_sel_hi:[1,0]
	v_pk_mul_f32 v[32:33], v[32:33], v[52:53] op_sel_hi:[1,0]
	v_cvt_pk_bf16_f32 v41, v46, v47
	v_cvt_pk_bf16_f32 v42, v50, v51
	v_cvt_pk_bf16_f32 v43, v54, v55
	v_lshl_add_u64 v[44:45], v[44:45], 0, v[146:147]
	v_pk_mul_f32 v[38:39], v[38:39], v[52:53] op_sel_hi:[1,0]
	v_max_f32_e32 v36, 0, v36
	v_max_f32_e32 v32, 0, v32
	v_max_f32_e32 v37, 0, v37
	v_max_f32_e32 v33, 0, v33
	v_max_f32_e32 v34, 0, v34
	v_max_f32_e32 v35, 0, v35
	global_store_dwordx4 v[44:45], v[40:43], off
	v_pk_mul_f32 v[36:37], v[36:37], v[36:37]
	s_nop 0
	v_pk_mul_f32 v[40:41], v[32:33], v[32:33]
	v_max_f32_e32 v32, 0, v38
	v_max_f32_e32 v33, 0, v39
	v_pk_mul_f32 v[42:43], v[34:35], v[34:35]
	v_fmamk_f32 v35, v246, 0x3a800000, v164
	v_pk_mul_f32 v[38:39], v[32:33], v[32:33]
	v_cvt_pk_bf16_f32 v32, v36, v37
	v_rsq_f32_e32 v36, v35
	v_cvt_pk_bf16_f32 v33, v38, v39
	v_cvt_pk_bf16_f32 v34, v40, v41
	v_cvt_pk_bf16_f32 v35, v42, v43
	v_pk_mul_f32 v[28:29], v[28:29], v[36:37] op_sel_hi:[1,0]
	v_pk_mul_f32 v[24:25], v[24:25], v[36:37] op_sel_hi:[1,0]
	v_pk_mul_f32 v[30:31], v[30:31], v[36:37] op_sel_hi:[1,0]
	v_pk_mul_f32 v[26:27], v[26:27], v[36:37] op_sel_hi:[1,0]
	v_max_f32_e32 v28, 0, v28
	v_max_f32_e32 v24, 0, v24
	v_max_f32_e32 v29, 0, v29
	v_max_f32_e32 v25, 0, v25
	global_store_dwordx4 v[44:45], v[32:35], off offset:256
	v_pk_mul_f32 v[28:29], v[28:29], v[28:29]
	v_max_f32_e32 v26, 0, v26
	v_lshlrev_b64 v[32:33], 13, v[148:149]
	v_pk_mul_f32 v[34:35], v[24:25], v[24:25]
	v_max_f32_e32 v24, 0, v30
	v_max_f32_e32 v25, 0, v31
	v_max_f32_e32 v27, 0, v27
	v_pk_mul_f32 v[30:31], v[24:25], v[24:25]
	v_pk_mul_f32 v[38:39], v[26:27], v[26:27]
	v_cvt_pk_bf16_f32 v24, v28, v29
	v_lshl_add_u64 v[28:29], s[68:69], 0, v[32:33]
	v_pk_mul_f32 v[20:21], v[20:21], v[36:37] op_sel_hi:[1,0]
	v_pk_mul_f32 v[18:19], v[18:19], v[36:37] op_sel_hi:[1,0]
	v_pk_mul_f32 v[16:17], v[16:17], v[36:37] op_sel_hi:[1,0]
	v_cvt_pk_bf16_f32 v25, v30, v31
	v_cvt_pk_bf16_f32 v26, v34, v35
	v_cvt_pk_bf16_f32 v27, v38, v39
	v_lshl_add_u64 v[28:29], v[28:29], 0, v[146:147]
	v_pk_mul_f32 v[22:23], v[22:23], v[36:37] op_sel_hi:[1,0]
	v_max_f32_e32 v20, 0, v20
	v_max_f32_e32 v16, 0, v16
	v_max_f32_e32 v21, 0, v21
	v_max_f32_e32 v17, 0, v17
	v_max_f32_e32 v18, 0, v18
	v_max_f32_e32 v19, 0, v19
	global_store_dwordx4 v[28:29], v[24:27], off
	v_pk_mul_f32 v[20:21], v[20:21], v[20:21]
	s_nop 0
	v_pk_mul_f32 v[24:25], v[16:17], v[16:17]
	v_max_f32_e32 v16, 0, v22
	v_max_f32_e32 v17, 0, v23
	v_pk_mul_f32 v[26:27], v[18:19], v[18:19]
	v_fmamk_f32 v19, v247, 0x3a800000, v164
	v_pk_mul_f32 v[22:23], v[16:17], v[16:17]
	v_cvt_pk_bf16_f32 v16, v20, v21
	v_rsq_f32_e32 v20, v19
	v_cvt_pk_bf16_f32 v17, v22, v23
	v_cvt_pk_bf16_f32 v18, v24, v25
	v_cvt_pk_bf16_f32 v19, v26, v27
	v_pk_mul_f32 v[12:13], v[12:13], v[20:21] op_sel_hi:[1,0]
	v_pk_mul_f32 v[8:9], v[8:9], v[20:21] op_sel_hi:[1,0]
	v_pk_mul_f32 v[14:15], v[14:15], v[20:21] op_sel_hi:[1,0]
	v_pk_mul_f32 v[10:11], v[10:11], v[20:21] op_sel_hi:[1,0]
	v_max_f32_e32 v12, 0, v12
	v_max_f32_e32 v8, 0, v8
	v_max_f32_e32 v13, 0, v13
	v_max_f32_e32 v9, 0, v9
	global_store_dwordx4 v[28:29], v[16:19], off offset:256
	v_pk_mul_f32 v[12:13], v[12:13], v[12:13]
	v_max_f32_e32 v10, 0, v10
	v_lshlrev_b64 v[16:17], 13, v[144:145]
	v_pk_mul_f32 v[18:19], v[8:9], v[8:9]
	v_max_f32_e32 v8, 0, v14
	v_max_f32_e32 v9, 0, v15
	v_max_f32_e32 v11, 0, v11
	v_pk_mul_f32 v[14:15], v[8:9], v[8:9]
	v_pk_mul_f32 v[22:23], v[10:11], v[10:11]
	v_cvt_pk_bf16_f32 v8, v12, v13
	v_lshl_add_u64 v[12:13], s[68:69], 0, v[16:17]
	v_pk_mul_f32 v[0:1], v[0:1], v[20:21] op_sel_hi:[1,0]
	v_cvt_pk_bf16_f32 v9, v14, v15
	v_cvt_pk_bf16_f32 v10, v18, v19
	v_cvt_pk_bf16_f32 v11, v22, v23
	v_lshl_add_u64 v[12:13], v[12:13], 0, v[146:147]
	v_pk_mul_f32 v[6:7], v[6:7], v[20:21] op_sel_hi:[1,0]
	v_pk_mul_f32 v[4:5], v[4:5], v[20:21] op_sel_hi:[1,0]
	v_pk_mul_f32 v[2:3], v[2:3], v[20:21] op_sel_hi:[1,0]
	v_max_f32_e32 v0, 0, v0
	v_max_f32_e32 v1, 0, v1
	global_store_dwordx4 v[12:13], v[8:11], off
	v_max_f32_e32 v4, 0, v4
	v_max_f32_e32 v5, 0, v5
	v_pk_mul_f32 v[8:9], v[0:1], v[0:1]
	v_max_f32_e32 v0, 0, v6
	v_max_f32_e32 v2, 0, v2
	v_max_f32_e32 v1, 0, v7
	v_max_f32_e32 v3, 0, v3
	v_pk_mul_f32 v[4:5], v[4:5], v[4:5]
	v_pk_mul_f32 v[6:7], v[0:1], v[0:1]
	v_pk_mul_f32 v[10:11], v[2:3], v[2:3]
	v_cvt_pk_bf16_f32 v0, v4, v5
	v_cvt_pk_bf16_f32 v1, v6, v7
	v_cvt_pk_bf16_f32 v2, v8, v9
	v_cvt_pk_bf16_f32 v3, v10, v11
	global_store_dwordx4 v[12:13], v[0:3], off offset:256
	s_cbranch_vccnz .LBB0_1484
	s_andn2_b64 vcc, exec, s[2:3]
	s_cbranch_vccnz .LBB0_1483
	s_barrier
	s_branch .LBB0_1483

	.amdhsa_kernel _Z8yoco_fwd4Args
		.amdhsa_group_segment_fixed_size 0
		.amdhsa_private_segment_fixed_size 0
		.amdhsa_kernarg_size 536
		.amdhsa_user_sgpr_count 2
		.amdhsa_user_sgpr_dispatch_ptr 0
		.amdhsa_user_sgpr_queue_ptr 0
		.amdhsa_user_sgpr_kernarg_segment_ptr 1
		.amdhsa_user_sgpr_dispatch_id 0
		.amdhsa_user_sgpr_kernarg_preload_length 0
		.amdhsa_user_sgpr_kernarg_preload_offset 0
		.amdhsa_user_sgpr_private_segment_size 0
		.amdhsa_uses_dynamic_stack 0
		.amdhsa_enable_private_segment 0
		.amdhsa_system_sgpr_workgroup_id_x 1
		.amdhsa_system_sgpr_workgroup_id_y 0
		.amdhsa_system_sgpr_workgroup_id_z 0
		.amdhsa_system_sgpr_workgroup_info 0
		.amdhsa_system_vgpr_workitem_id 2
		.amdhsa_next_free_vgpr 256
		.amdhsa_next_free_sgpr 102
		.amdhsa_accum_offset 256
		.amdhsa_reserve_vcc 1
		.amdhsa_float_round_mode_32 0
		.amdhsa_float_round_mode_16_64 0
		.amdhsa_float_denorm_mode_32 3
		.amdhsa_float_denorm_mode_16_64 3
		.amdhsa_dx10_clamp 1
		.amdhsa_ieee_mode 1
		.amdhsa_fp16_overflow 0
		.amdhsa_tg_split 0
		.amdhsa_exception_fp_ieee_invalid_op 0
		.amdhsa_exception_fp_denorm_src 0
		.amdhsa_exception_fp_ieee_div_zero 0
		.amdhsa_exception_fp_ieee_overflow 0
		.amdhsa_exception_fp_ieee_underflow 0
		.amdhsa_exception_fp_ieee_inexact 0
		.amdhsa_exception_int_div_zero 0
	.end_amdhsa_kernel

amdhsa.kernels:
  - .agpr_count:     0
    .args:
      - .offset:         0
        .size:           280
        .value_kind:     by_value
      - .offset:         280
        .size:           4
        .value_kind:     hidden_block_count_x
      - .offset:         284
        .size:           4
        .value_kind:     hidden_block_count_y
      - .offset:         288
        .size:           4
        .value_kind:     hidden_block_count_z
      - .offset:         292
        .size:           2
        .value_kind:     hidden_group_size_x
      - .offset:         294
        .size:           2
        .value_kind:     hidden_group_size_y
      - .offset:         296
        .size:           2
        .value_kind:     hidden_group_size_z
      - .offset:         298
        .size:           2
        .value_kind:     hidden_remainder_x
      - .offset:         300
        .size:           2
        .value_kind:     hidden_remainder_y
      - .offset:         302
        .size:           2
        .value_kind:     hidden_remainder_z
      - .offset:         320
        .size:           8
        .value_kind:     hidden_global_offset_x
      - .offset:         328
        .size:           8
        .value_kind:     hidden_global_offset_y
      - .offset:         336
        .size:           8
        .value_kind:     hidden_global_offset_z
      - .offset:         344
        .size:           2
        .value_kind:     hidden_grid_dims
      - .offset:         368
        .size:           8
        .value_kind:     hidden_multigrid_sync_arg
      - .offset:         400
        .size:           4
        .value_kind:     hidden_dynamic_lds_size
    .group_segment_fixed_size: 0
    .kernarg_segment_align: 8
    .kernarg_segment_size: 536
    .language:       OpenCL C
    .language_version:
      - 2
      - 0
    .max_flat_workgroup_size: 512
    .name:           _Z8yoco_fwd4Args
    .private_segment_fixed_size: 0
    .sgpr_count:     108
    .sgpr_spill_count: 55
    .symbol:         _Z8yoco_fwd4Args.kd
    .uniform_work_group_size: 1
    .uses_dynamic_stack: false
    .vgpr_count:     256
    .vgpr_spill_count: 0
    .wavefront_size: 64
